# v025 + z-gate tile staged in LDS by LDS-DMA (cross prompt units: last tile iteration; attention: drain iteration) and epilogue 2-byte global loads replaced by ds_read_u16; vmcnt waits in those epilogu
# baseline (speedup 1.0000x reference)
; DI float bf2f(unsigned short u) { return __uint_as_float((unsigned)u << 16); }
; DI unsigned f2bf(float f) { unsigned u = __float_as_uint(f); return (u + 0x7fffu + ((u >> 16) & 1u)) >> 16; }
; DI void attn_unit(Ctx A_, LAS unsigned char* lds, int b, int h, int qb, float lam, int wave, int lane) {
;     ...
;         asm volatile("s_waitcnt vmcnt(0) lgkmcnt(0)" ::: "memory");
;         __builtin_amdgcn_s_barrier(); asm volatile("" ::: "memory");
;         if (t + 2 < NT) load_tile(lds + ((t + 2) & 3) * BUF, Kg, Vg, (t + 2) * 64, wave, lane);
;     ...
;                 Y_[rw * YLD + C_YA + h_e * 128 + nb * 32 + r_e] = (bf16)f2bf(o[nb][i] * ssq[i] * sn * bf2f(P[rw * PLD + C_ZA + h_e * 128 + nb * 32 + r_e]));
.LBB0_872:
	s_waitcnt vmcnt(0) lgkmcnt(0)
	s_barrier
	s_sub_u32 s98, s67, s65
	s_cmp_eq_u32 s98, 2
	s_cbranch_scc0 .Lattn_zskip
	v_readfirstlane_b32 s100, v0
	s_cmpk_gt_u32 s100, 0xff
	s_cbranch_scc1 .Lattn_zskip
	s_or_b32 s98, s64, s0
	s_mul_hi_u32 s99, s98, 0x5800
	s_mul_i32 s98, s98, 0x5800
	v_readlane_b32 s101, v255, 9
	v_and_b32_e32 v206, 63, v0
	s_add_u32 s98, s98, s101
	v_readlane_b32 s101, v255, 10
	v_lshrrev_b32_e32 v207, 4, v206
	s_addc_u32 s99, s99, s101
	s_lshl_b32 s101, s63, 8
	s_addk_i32 s101, 0x1800
	s_add_u32 s98, s98, s101
	s_addc_u32 s99, s99, 0
	s_lshr_b32 s100, s100, 6
	s_lshl_b32 s100, s100, 13
	s_add_u32 s100, s100, 0x10000
	v_mul_u32_u24_e32 v207, 0x5800, v207
	v_and_b32_e32 v206, 15, v206
	v_lshl_or_b32 v206, v206, 4, v207
	s_mov_b32 m0, s100
	s_nop 0
	global_load_lds_dwordx4 v206, s[98:99]
	s_add_u32 s98, s98, 0x16000
	s_addc_u32 s99, s99, 0
	s_add_u32 s100, s100, 0x400
	s_mov_b32 m0, s100
	s_nop 0
	global_load_lds_dwordx4 v206, s[98:99]
	s_add_u32 s98, s98, 0x16000
	s_addc_u32 s99, s99, 0
	s_add_u32 s100, s100, 0x400
	s_mov_b32 m0, s100
	s_nop 0
	global_load_lds_dwordx4 v206, s[98:99]
	s_add_u32 s98, s98, 0x16000
	s_addc_u32 s99, s99, 0
	s_add_u32 s100, s100, 0x400
	s_mov_b32 m0, s100
	s_nop 0
	global_load_lds_dwordx4 v206, s[98:99]
	s_add_u32 s98, s98, 0x16000
	s_addc_u32 s99, s99, 0
	s_add_u32 s100, s100, 0x400
	s_mov_b32 m0, s100
	s_nop 0
	global_load_lds_dwordx4 v206, s[98:99]
	s_add_u32 s98, s98, 0x16000
	s_addc_u32 s99, s99, 0
	s_add_u32 s100, s100, 0x400
	s_mov_b32 m0, s100
	s_nop 0
	global_load_lds_dwordx4 v206, s[98:99]
	s_add_u32 s98, s98, 0x16000
	s_addc_u32 s99, s99, 0
	s_add_u32 s100, s100, 0x400
	s_mov_b32 m0, s100
	s_nop 0
	global_load_lds_dwordx4 v206, s[98:99]
	s_add_u32 s98, s98, 0x16000
	s_addc_u32 s99, s99, 0
	s_add_u32 s100, s100, 0x400
	s_mov_b32 m0, s100
	s_nop 0
	global_load_lds_dwordx4 v206, s[98:99]
.Lattn_zskip:
	s_cmp_ge_u32 s67, s65
	s_cbranch_scc1 .LBB0_874
	s_add_i32 s4, s66, 0x10000
	s_and_b32 s4, s4, 0x18000
	s_add_i32 s4, s4, 0
	s_add_i32 s5, s4, s33
	v_lshl_add_u64 v[82:83], s[12:13], 1, v[202:203]
	s_mov_b32 s6, m0
	s_mov_b32 m0, s5
	s_nop 0
	global_load_lds_dwordx4 v[82:83], off
	s_mov_b32 m0, s6
	s_add_i32 s5, s4, s38
	s_add_i32 s4, s4, s30
	v_lshl_add_u64 v[82:83], s[16:17], 1, v[202:203]
	s_mov_b32 s6, m0
	s_mov_b32 m0, s5
	s_nop 0
	global_load_lds_dwordx4 v[82:83], off
	s_mov_b32 m0, s6
	s_add_i32 s5, s4, s34
	s_addk_i32 s5, 0x4000
	s_mov_b32 s6, m0
	s_mov_b32 m0, s5
	s_nop 0
	global_load_lds_dwordx4 v[200:201], off
	s_mov_b32 m0, s6
	s_add_i32 s4, s4, s43
	s_addk_i32 s4, 0x4000
	s_mov_b32 s5, m0
	s_mov_b32 m0, s4
	s_nop 0
	global_load_lds_dwordx4 v[198:199], off
	s_mov_b32 m0, s5

; DI float bf2f(unsigned short u) { return __uint_as_float((unsigned)u << 16); }
; DI unsigned f2bf(float f) { unsigned u = __float_as_uint(f); return (u + 0x7fffu + ((u >> 16) & 1u)) >> 16; }
; DI int crow(int i, int hh) { return (i & 3) + 8 * (i >> 2) + 4 * hh; }
; DI void attn_unit(Ctx A_, LAS unsigned char* lds, int b, int h, int qb, float lam, int wave, int lane) {
;     ...
;     if (mp == 0) {
;         float ssq[16];
; #pragma unroll
;         for (int i = 0; i < 16; ++i) ssq[i] = 0.f;
; #pragma unroll
;         for (int nb = 0; nb < 4; ++nb)
; #pragma unroll
;             for (int i = 0; i < 16; ++i) { const float d = o[nb][i] - X2[(nb * 16 + i) * 64]; o[nb][i] = d; ssq[i] += d * d; }
; #pragma unroll
;         for (int i = 0; i < 16; ++i) {
;             float v = ssq[i];
; #pragma unroll
;             for (int x = 1; x < 32; x <<= 1) v += __shfl_xor(v, x);
;             ssq[i] = ONE_M_LAMINIT / sqrtf(v * (1.0f / 128.0f) + NORM_EPS);
;         }
; #pragma unroll
;         for (int nb = 0; nb < 4; ++nb) {
;             const float sn = SUB_NORM[nb * 32 + r_e];
; #pragma unroll
;             for (int i = 0; i < 16; ++i) {
;                 const size_t rw = (size_t)(rowq_e + crow(i, hh_e));
;                 Y_[rw * YLD + C_YA + h_e * 128 + nb * 32 + r_e] = (bf16)f2bf(o[nb][i] * ssq[i] * sn * bf2f(P[rw * PLD + C_ZA + h_e * 128 + nb * 32 + r_e]));
.LBB0_894:
	s_waitcnt lgkmcnt(0)
	s_barrier
	v_readlane_b32 s4, v255, 36
	v_readlane_b32 s5, v255, 37
	s_andn2_b64 vcc, exec, s[4:5]
	s_cbranch_vccnz .LBB0_862
	s_mul_i32 s99, s0, 0x5800
	v_readlane_b32 s98, v255, 9
	s_add_u32 s99, s99, s98
	s_lshl_b32 s98, s63, 8
	s_add_u32 s99, s99, s98
	s_addk_i32 s99, 0x1800
	s_sub_u32 s99, 0, s99
	s_add_u32 s98, s99, 0x800
	v_readfirstlane_b32 s100, v0
	s_lshr_b32 s100, s100, 6
	s_lshl_b32 s100, s100, 13
	s_add_u32 s100, s100, 0x10000
	s_mov_b32 s101, 0x2e8bb
	ds_read2st64_b32 v[4:5], v64 offset1:1
	ds_read2st64_b32 v[24:25], v64 offset0:2 offset1:3
	ds_read2st64_b32 v[18:19], v64 offset0:4 offset1:5
	ds_read2st64_b32 v[16:17], v64 offset0:6 offset1:7
	ds_read2st64_b32 v[32:33], v64 offset0:16 offset1:17
	s_waitcnt lgkmcnt(4)
	v_sub_f32_e32 v104, v34, v4
	ds_read2st64_b32 v[26:27], v64 offset0:18 offset1:19
	ds_read2st64_b32 v[14:15], v64 offset0:20 offset1:21
	ds_read2st64_b32 v[10:11], v64 offset0:22 offset1:23
	v_readlane_b32 s64, v254, 22
	v_readlane_b32 s74, v254, 32
	s_waitcnt lgkmcnt(3)
	v_sub_f32_e32 v97, v35, v32
	ds_read2st64_b32 v[34:35], v64 offset0:32 offset1:33
	ds_read2st64_b32 v[28:29], v64 offset0:34 offset1:35
	ds_read2st64_b32 v[20:21], v64 offset0:36 offset1:37
	ds_read2st64_b32 v[8:9], v64 offset0:38 offset1:39
	v_readlane_b32 s75, v254, 33
	v_mul_f32_e32 v3, v97, v97
	v_fmac_f32_e32 v3, v104, v104
	s_waitcnt lgkmcnt(3)
	v_sub_f32_e32 v98, v36, v34
	ds_read2st64_b32 v[36:37], v64 offset0:48 offset1:49
	ds_read2st64_b32 v[30:31], v64 offset0:50 offset1:51
	ds_read2st64_b32 v[22:23], v64 offset0:52 offset1:53
	ds_read2st64_b32 v[12:13], v64 offset0:54 offset1:55
	v_fmac_f32_e32 v3, v98, v98
	v_readlane_b32 s4, v255, 9
	v_readlane_b32 s5, v255, 10
	s_waitcnt lgkmcnt(3)
	v_sub_f32_e32 v99, v2, v36
	v_lshl_add_u32 v36, v197, 2, s0
	v_ashrrev_i32_e32 v197, 31, v196
	v_lshl_add_u64 v[38:39], v[196:197], 2, s[74:75]
	global_load_dword v34, v[38:39], off
	v_fmac_f32_e32 v3, v99, v99
	s_nop 1
	v_mov_b32_dpp v2, v3 quad_perm:[1,0,3,2] row_mask:0xf bank_mask:0xf
	s_lshl_b32 s0, s63, 7
	s_ashr_i32 s1, s0, 31
	v_mov_b64_e32 v[6:7], s[4:5]
	s_lshl_b64 s[0:1], s[0:1], 1
	v_mad_i64_i32 v[106:107], s[4:5], v36, s57, v[6:7]
	s_waitcnt lgkmcnt(0)
	v_add_f32_e32 v4, v3, v2
	v_lshlrev_b64 v[2:3], 1, v[196:197]
	v_lshl_add_u64 v[106:107], v[106:107], 0, s[0:1]
	v_lshl_add_u64 v[110:111], v[106:107], 0, v[2:3]
	v_add_co_u32_e32 v106, vcc, s60, v110
	s_nop 1
	v_mov_b32_dpp v32, v4 quad_perm:[2,3,0,1] row_mask:0xf bank_mask:0xf
	s_nop 0
	v_addc_co_u32_e32 v107, vcc, 0, v111, vcc
	v_add_u32_e32 v206, s98, v106
	v_mul_hi_u32 v207, v206, s101
	v_mul_u32_u24_e32 v207, 0x5700, v207
	v_sub_u32_e32 v206, v206, v207
	v_add_u32_e32 v206, s100, v206
	ds_read_u16 v107, v206
	v_sub_f32_e32 v106, v100, v5
	s_waitcnt lgkmcnt(0)
	v_add_f32_e32 v4, v4, v32
	s_nop 1
	v_mov_b32_dpp v32, v4 row_half_mirror row_mask:0xf bank_mask:0xf
	v_sub_f32_e32 v105, v101, v33
	v_sub_f32_e32 v100, v102, v35
	v_sub_f32_e32 v101, v103, v37
	v_sub_f32_e32 v24, v93, v24
	s_waitcnt lgkmcnt(0)
	v_add_f32_e32 v4, v4, v32
	s_nop 1
	v_mov_b32_dpp v32, v4 row_mirror row_mask:0xf bank_mask:0xf
	v_sub_f32_e32 v30, v96, v30
	v_sub_f32_e32 v89, v89, v25
	v_sub_f32_e32 v91, v91, v29
	v_sub_f32_e32 v92, v92, v31
	s_waitcnt lgkmcnt(0)
	v_add_f32_e32 v4, v4, v32
	ds_bpermute_b32 v5, v209, v4
	v_mul_f32_e32 v32, v105, v105
	v_fmac_f32_e32 v32, v106, v106
	v_fmac_f32_e32 v32, v100, v100
	v_fmac_f32_e32 v32, v101, v101
	s_waitcnt lgkmcnt(0)
	v_add_f32_e32 v4, v4, v5
	v_fmamk_f32 v4, v4, 0x3c000000, v211
	v_mul_f32_e32 v5, 0x4f800000, v4
	v_cmp_gt_f32_e32 vcc, s58, v4
	v_sub_f32_e32 v90, v90, v27
	v_mul_f32_e32 v27, v90, v90
	v_cndmask_b32_e32 v4, v4, v5, vcc
	v_sqrt_f32_e32 v5, v4
	v_fmac_f32_e32 v27, v89, v89
	v_fmac_f32_e32 v27, v91, v91
	v_fmac_f32_e32 v27, v92, v92
	v_add_u32_e32 v33, -1, v5
	v_fma_f32 v35, -v33, v5, v4
	v_cmp_ge_f32_e64 s[4:5], 0, v35
	v_add_u32_e32 v35, 1, v5
	v_sub_f32_e32 v88, v88, v18
	v_cndmask_b32_e64 v33, v5, v33, s[4:5]
	v_fma_f32 v5, -v35, v5, v4
	v_cmp_lt_f32_e64 s[4:5], 0, v5
	v_sub_f32_e32 v84, v84, v16
	v_sub_f32_e32 v83, v83, v19
	v_cndmask_b32_e64 v5, v33, v35, s[4:5]
	s_nop 1
	v_mov_b32_dpp v35, v32 quad_perm:[1,0,3,2] row_mask:0xf bank_mask:0xf
	v_mul_f32_e32 v33, 0x37800000, v5
	v_cndmask_b32_e32 v5, v5, v33, vcc
	v_cmp_class_f32_e32 vcc, v4, v212
	v_sub_f32_e32 v86, v86, v20
	s_waitcnt lgkmcnt(0)
	v_add_f32_e32 v32, v32, v35
	v_cndmask_b32_e32 v4, v5, v4, vcc
	v_div_scale_f32 v5, s[4:5], v4, v4, s59
	s_nop 1
	v_mov_b32_dpp v35, v32 quad_perm:[2,3,0,1] row_mask:0xf bank_mask:0xf
	v_rcp_f32_e32 v33, v5
	s_add_u32 s4, s51, s0
	s_addc_u32 s5, s52, s1
	v_sub_f32_e32 v85, v85, v14
	v_fma_f32 v37, -v5, v33, 1.0
	s_waitcnt lgkmcnt(0)
	v_add_f32_e32 v32, v32, v35
	v_fmac_f32_e32 v33, v37, v33
	v_div_scale_f32 v37, vcc, s59, v4, s59
	s_nop 1
	v_mov_b32_dpp v35, v32 row_half_mirror row_mask:0xf bank_mask:0xf
	v_mul_f32_e32 v102, v37, v33
	v_fma_f32 v103, -v5, v102, v37
	v_fmac_f32_e32 v102, v103, v33
	v_fma_f32 v5, -v5, v102, v37
	v_div_fmas_f32 v5, v5, v33, v102
	s_waitcnt lgkmcnt(0)
	v_add_f32_e32 v103, v32, v35
	v_lshl_add_u64 v[32:33], v[110:111], 0, s[20:21]
	global_load_dword v35, v[38:39], off offset:128
	v_add_u32_e32 v206, s99, v32
	v_mul_hi_u32 v207, v206, s101
	v_mul_u32_u24_e32 v207, 0x5700, v207
	v_sub_u32_e32 v206, v206, v207
	v_add_u32_e32 v206, s100, v206
	ds_read_u16 v109, v206 offset:64
	global_load_dword v37, v[38:39], off offset:256
	s_nop 0
	global_load_dword v38, v[38:39], off offset:384
	s_waitcnt vmcnt(0)
	v_div_fixup_f32 v102, v5, v4, s59
	v_mul_f32_e32 v104, v104, v102
	s_waitcnt lgkmcnt(0)
; DI float bf2f(unsigned short u) { return __uint_as_float((unsigned)u << 16); }
; DI unsigned f2bf(float f) { unsigned u = __float_as_uint(f); return (u + 0x7fffu + ((u >> 16) & 1u)) >> 16; }
; DI int crow(int i, int hh) { return (i & 3) + 8 * (i >> 2) + 4 * hh; }
; DI void attn_unit(Ctx A_, LAS unsigned char* lds, int b, int h, int qb, float lam, int wave, int lane) {
;     ...
;         for (int i = 0; i < 16; ++i) {
;             float v = ssq[i];
; #pragma unroll
;             for (int x = 1; x < 32; x <<= 1) v += __shfl_xor(v, x);
;             ssq[i] = ONE_M_LAMINIT / sqrtf(v * (1.0f / 128.0f) + NORM_EPS);
;         }
; #pragma unroll
;         for (int nb = 0; nb < 4; ++nb) {
;             const float sn = SUB_NORM[nb * 32 + r_e];
; #pragma unroll
;             for (int i = 0; i < 16; ++i) {
;                 const size_t rw = (size_t)(rowq_e + crow(i, hh_e));
;                 Y_[rw * YLD + C_YA + h_e * 128 + nb * 32 + r_e] = (bf16)f2bf(o[nb][i] * ssq[i] * sn * bf2f(P[rw * PLD + C_ZA + h_e * 128 + nb * 32 + r_e]));
	v_mul_f32_e32 v39, v104, v34
	v_add_u32_e32 v206, s99, v32
	v_mul_hi_u32 v207, v206, s101
	v_mul_u32_u24_e32 v207, 0x5700, v207
	v_sub_u32_e32 v206, v206, v207
	v_add_u32_e32 v206, s100, v206
	ds_read_u16 v104, v206 offset:128
	v_add_u32_e32 v206, s99, v32
	v_mul_hi_u32 v207, v206, s101
	v_mul_u32_u24_e32 v207, 0x5700, v207
	v_sub_u32_e32 v206, v206, v207
	v_add_u32_e32 v206, s100, v206
	ds_read_u16 v114, v206 offset:192
	v_lshl_add_u64 v[4:5], s[4:5], 0, v[2:3]
	s_nop 1
	v_mov_b32_dpp v108, v103 row_mirror row_mask:0xf bank_mask:0xf
	v_mul_f32_e32 v97, v97, v102
	v_mul_f32_e32 v14, v85, v85
	v_fmac_f32_e32 v14, v88, v88
	v_fmac_f32_e32 v14, v86, v86
	s_waitcnt lgkmcnt(0)
	v_lshlrev_b32_e32 v32, 16, v107
	v_mul_f32_e32 v32, v39, v32
	v_bfe_u32 v33, v32, 16, 1
	v_add3_u32 v39, v32, v33, s61
	v_mad_i64_i32 v[32:33], s[4:5], v36, s62, v[4:5]
	global_store_short_d16_hi v[32:33], v39, off
	v_add_u32_e32 v39, 1, v36
	v_mad_i64_i32 v[110:111], s[4:5], v39, s57, v[6:7]
	v_lshl_add_u64 v[110:111], v[110:111], 0, s[0:1]
	v_lshl_add_u64 v[110:111], v[110:111], 0, v[2:3]
	v_add_co_u32_e32 v112, vcc, s60, v110
	s_waitcnt lgkmcnt(0)
	v_add_f32_e32 v93, v103, v108
	v_addc_co_u32_e32 v113, vcc, 0, v111, vcc
	v_add_u32_e32 v206, s98, v112
	v_mul_hi_u32 v207, v206, s101
	v_mul_u32_u24_e32 v207, 0x5700, v207
	v_sub_u32_e32 v206, v206, v207
	v_add_u32_e32 v206, s100, v206
	ds_read_u16 v107, v206
	ds_bpermute_b32 v103, v209, v93
	v_sub_f32_e32 v112, v95, v28
	v_sub_f32_e32 v108, v94, v26
	v_mul_f32_e32 v26, v108, v108
	v_fmac_f32_e32 v26, v24, v24
	s_waitcnt lgkmcnt(0)
	v_add_f32_e32 v28, v93, v103
	v_fmamk_f32 v28, v28, 0x3c000000, v211
	v_mul_f32_e32 v93, 0x4f800000, v28
	v_cmp_gt_f32_e32 vcc, s58, v28
	v_fmac_f32_e32 v26, v112, v112
	v_fmac_f32_e32 v26, v30, v30
	v_cndmask_b32_e32 v28, v28, v93, vcc
	v_sqrt_f32_e32 v93, v28
	v_sub_f32_e32 v87, v87, v22
	v_fmac_f32_e32 v14, v87, v87
	v_sub_f32_e32 v82, v82, v17
	v_add_u32_e32 v94, -1, v93
	v_fma_f32 v95, -v94, v93, v28
	v_cmp_ge_f32_e64 s[4:5], 0, v95
	v_add_u32_e32 v95, 1, v93
	v_readlane_b32 s65, v254, 23
	v_cndmask_b32_e64 v94, v93, v94, s[4:5]
	v_fma_f32 v93, -v95, v93, v28
	v_cmp_lt_f32_e64 s[4:5], 0, v93
	v_readlane_b32 s66, v254, 24
	v_readlane_b32 s67, v254, 25
	v_cndmask_b32_e64 v93, v94, v95, s[4:5]
	v_mul_f32_e32 v94, 0x37800000, v93
	v_cndmask_b32_e32 v93, v93, v94, vcc
	v_cmp_class_f32_e32 vcc, v28, v212
	s_nop 1
	v_mov_b32_dpp v95, v26 quad_perm:[1,0,3,2] row_mask:0xf bank_mask:0xf
	v_readlane_b32 s68, v254, 26
	v_cndmask_b32_e32 v28, v93, v28, vcc
	v_div_scale_f32 v93, s[4:5], v28, v28, s59
	v_rcp_f32_e32 v94, v93
	s_waitcnt lgkmcnt(0)
	v_add_f32_e32 v26, v26, v95
	s_nop 1
	v_mov_b32_dpp v95, v26 quad_perm:[2,3,0,1] row_mask:0xf bank_mask:0xf
	v_readlane_b32 s69, v254, 27
	v_fma_f32 v96, -v93, v94, 1.0
	v_fmac_f32_e32 v94, v96, v94
	v_div_scale_f32 v96, vcc, s59, v28, s59
	v_mul_f32_e32 v103, v96, v94
	v_fma_f32 v113, -v93, v103, v96
	v_fmac_f32_e32 v103, v113, v94
	v_fma_f32 v93, -v93, v103, v96
	v_div_fmas_f32 v93, v93, v94, v103
	s_waitcnt lgkmcnt(0)
	v_mul_f32_e32 v97, v97, v35
	s_waitcnt lgkmcnt(0)
	v_lshlrev_b32_e32 v103, 16, v109
	v_mul_f32_e32 v97, v97, v103
	s_waitcnt lgkmcnt(0)
	v_add_f32_e32 v26, v26, v95
	v_bfe_u32 v103, v97, 16, 1
	s_nop 1
	v_mov_b32_dpp v95, v26 row_half_mirror row_mask:0xf bank_mask:0xf
	v_add3_u32 v97, v97, v103, s61
	global_store_short_d16_hi v[32:33], v97, off offset:64
	v_mul_f32_e32 v97, v98, v102
	s_waitcnt lgkmcnt(0)
	v_mul_f32_e32 v97, v97, v37
	s_waitcnt lgkmcnt(0)
	v_lshlrev_b32_e32 v98, 16, v104
	v_div_fixup_f32 v28, v93, v28, s59
	v_mul_f32_e32 v97, v97, v98
	v_mul_f32_e32 v94, v106, v28
	v_bfe_u32 v98, v97, 16, 1
	s_waitcnt lgkmcnt(0)
	v_add_f32_e32 v26, v26, v95
	v_mul_f32_e32 v96, v94, v34
	v_lshl_add_u64 v[94:95], v[110:111], 0, s[20:21]
	v_add3_u32 v97, v97, v98, s61
	v_add_u32_e32 v206, s99, v94
	v_mul_hi_u32 v207, v206, s101
	v_mul_u32_u24_e32 v207, 0x5700, v207
	v_sub_u32_e32 v206, v206, v207
	v_add_u32_e32 v206, s100, v206
	ds_read_u16 v103, v206 offset:64
	s_waitcnt lgkmcnt(0)
	v_lshlrev_b32_e32 v98, 16, v114
	global_store_short_d16_hi v[32:33], v97, off offset:128
	v_mul_f32_e32 v97, v99, v102
	v_mul_f32_e32 v97, v97, v38
	v_mul_f32_e32 v97, v97, v98
	v_bfe_u32 v98, v97, 16, 1
	v_add3_u32 v97, v97, v98, s61
	global_store_short_d16_hi v[32:33], v97, off offset:192
	v_add_u32_e32 v206, s99, v94
	v_mul_hi_u32 v207, v206, s101
	v_mul_u32_u24_e32 v207, 0x5700, v207
	v_sub_u32_e32 v206, v206, v207
	v_add_u32_e32 v206, s100, v206
	ds_read_u16 v98, v206 offset:128
	v_add_u32_e32 v206, s99, v94
	v_mul_hi_u32 v207, v206, s101
	v_mul_u32_u24_e32 v207, 0x5700, v207
	v_sub_u32_e32 v206, v206, v207
	v_add_u32_e32 v206, s100, v206
	ds_read_u16 v99, v206 offset:192
	s_nop 1
	v_mov_b32_dpp v93, v26 row_mirror row_mask:0xf bank_mask:0xf
	v_readlane_b32 s70, v254, 28
	s_waitcnt lgkmcnt(0)
	v_lshlrev_b32_e32 v32, 16, v107
	v_mul_f32_e32 v32, v96, v32
	v_bfe_u32 v33, v32, 16, 1
	v_add3_u32 v94, v32, v33, s61
	v_mad_i64_i32 v[32:33], s[4:5], v39, s62, v[4:5]
	v_add_u32_e32 v39, 2, v36
	global_store_short_d16_hi v[32:33], v94, off
	v_mad_i64_i32 v[94:95], s[4:5], v39, s57, v[6:7]
	v_lshl_add_u64 v[94:95], v[94:95], 0, s[0:1]
	v_lshl_add_u64 v[94:95], v[94:95], 0, v[2:3]
	v_add_co_u32_e32 v96, vcc, s60, v94
	s_waitcnt lgkmcnt(0)
	v_add_f32_e32 v25, v26, v93
	v_addc_co_u32_e32 v97, vcc, 0, v95, vcc
	v_add_u32_e32 v206, s98, v96
	v_mul_hi_u32 v207, v206, s101
	v_mul_u32_u24_e32 v207, 0x5700, v207
	v_sub_u32_e32 v206, v206, v207
	v_add_u32_e32 v206, s100, v206
	ds_read_u16 v96, v206
	ds_bpermute_b32 v26, v209, v25
	v_readlane_b32 s71, v254, 29
	v_readlane_b32 s72, v254, 30
	v_readlane_b32 s73, v254, 31
	v_readlane_b32 s76, v254, 34
	s_waitcnt lgkmcnt(0)
; DI float bf2f(unsigned short u) { return __uint_as_float((unsigned)u << 16); }
; DI unsigned f2bf(float f) { unsigned u = __float_as_uint(f); return (u + 0x7fffu + ((u >> 16) & 1u)) >> 16; }
; DI int crow(int i, int hh) { return (i & 3) + 8 * (i >> 2) + 4 * hh; }
; DI void attn_unit(Ctx A_, LAS unsigned char* lds, int b, int h, int qb, float lam, int wave, int lane) {
;     ...
;         for (int i = 0; i < 16; ++i) {
;             float v = ssq[i];
; #pragma unroll
;             for (int x = 1; x < 32; x <<= 1) v += __shfl_xor(v, x);
;             ssq[i] = ONE_M_LAMINIT / sqrtf(v * (1.0f / 128.0f) + NORM_EPS);
;         }
; #pragma unroll
;         for (int nb = 0; nb < 4; ++nb) {
;             const float sn = SUB_NORM[nb * 32 + r_e];
; #pragma unroll
;             for (int i = 0; i < 16; ++i) {
;                 const size_t rw = (size_t)(rowq_e + crow(i, hh_e));
;                 Y_[rw * YLD + C_YA + h_e * 128 + nb * 32 + r_e] = (bf16)f2bf(o[nb][i] * ssq[i] * sn * bf2f(P[rw * PLD + C_ZA + h_e * 128 + nb * 32 + r_e]));
	v_add_f32_e32 v25, v25, v26
	v_fmamk_f32 v25, v25, 0x3c000000, v211
	v_mul_f32_e32 v26, 0x4f800000, v25
	v_cmp_gt_f32_e32 vcc, s58, v25
	v_readlane_b32 s77, v254, 35
	v_readlane_b32 s78, v254, 36
	v_cndmask_b32_e32 v25, v25, v26, vcc
	v_sqrt_f32_e32 v26, v25
	v_readlane_b32 s79, v254, 37
	v_add_u32_e32 v29, -1, v26
	v_fma_f32 v31, -v29, v26, v25
	v_cmp_ge_f32_e64 s[4:5], 0, v31
	v_add_u32_e32 v31, 1, v26
	s_nop 0
	v_cndmask_b32_e64 v29, v26, v29, s[4:5]
	v_fma_f32 v26, -v31, v26, v25
	v_cmp_lt_f32_e64 s[4:5], 0, v26
	s_nop 1
	v_cndmask_b32_e64 v26, v29, v31, s[4:5]
	v_mul_f32_e32 v29, 0x37800000, v26
	v_cndmask_b32_e32 v26, v26, v29, vcc
	v_cmp_class_f32_e32 vcc, v25, v212
	s_nop 1
	v_mov_b32_dpp v31, v27 quad_perm:[1,0,3,2] row_mask:0xf bank_mask:0xf
	s_nop 0
	v_cndmask_b32_e32 v25, v26, v25, vcc
	v_div_scale_f32 v26, s[4:5], v25, v25, s59
	v_rcp_f32_e32 v29, v26
	s_nop 0
	v_fma_f32 v18, -v26, v29, 1.0
	v_fmac_f32_e32 v29, v18, v29
	s_waitcnt lgkmcnt(0)
	v_add_f32_e32 v18, v27, v31
	s_nop 1
	v_mov_b32_dpp v27, v18 quad_perm:[2,3,0,1] row_mask:0xf bank_mask:0xf
	v_div_scale_f32 v31, vcc, s59, v25, s59
	v_mul_f32_e32 v93, v31, v29
	v_fma_f32 v97, -v26, v93, v31
	s_waitcnt lgkmcnt(0)
	v_add_f32_e32 v18, v18, v27
	s_nop 1
	v_mov_b32_dpp v27, v18 row_half_mirror row_mask:0xf bank_mask:0xf
	v_fmac_f32_e32 v93, v97, v29
	v_fma_f32 v26, -v26, v93, v31
	v_div_fmas_f32 v26, v26, v29, v93
	s_waitcnt lgkmcnt(0)
	v_lshlrev_b32_e32 v29, 16, v103
	s_waitcnt lgkmcnt(0)
	v_add_f32_e32 v18, v18, v27
	v_mul_f32_e32 v27, v105, v28
	v_mul_f32_e32 v27, v27, v35
	v_mul_f32_e32 v27, v27, v29
	v_bfe_u32 v29, v27, 16, 1
	v_add3_u32 v27, v27, v29, s61
	global_store_short_d16_hi v[32:33], v27, off offset:64
	v_mul_f32_e32 v27, v100, v28
	v_mul_f32_e32 v27, v27, v37
	s_waitcnt lgkmcnt(0)
	v_lshlrev_b32_e32 v29, 16, v98
	v_div_fixup_f32 v31, v26, v25, s59
	v_mul_f32_e32 v27, v27, v29
	v_mul_f32_e32 v24, v24, v31
	v_bfe_u32 v29, v27, 16, 1
	v_mul_f32_e32 v26, v24, v34
	v_lshl_add_u64 v[24:25], v[94:95], 0, s[20:21]
	v_add3_u32 v27, v27, v29, s61
	v_add_u32_e32 v206, s99, v24
	v_mul_hi_u32 v207, v206, s101
	v_mul_u32_u24_e32 v207, 0x5700, v207
	v_sub_u32_e32 v206, v206, v207
	v_add_u32_e32 v206, s100, v206
	ds_read_u16 v94, v206 offset:64
	s_nop 1
	v_mov_b32_dpp v93, v18 row_mirror row_mask:0xf bank_mask:0xf
	global_store_short_d16_hi v[32:33], v27, off offset:128
	v_mul_f32_e32 v27, v101, v28
	v_mul_f32_e32 v27, v27, v38
	s_waitcnt lgkmcnt(0)
	v_lshlrev_b32_e32 v28, 16, v99
	v_mul_f32_e32 v27, v27, v28
	v_bfe_u32 v28, v27, 16, 1
	v_add3_u32 v27, v27, v28, s61
	global_store_short_d16_hi v[32:33], v27, off offset:192
	v_add_u32_e32 v206, s99, v24
	v_mul_hi_u32 v207, v206, s101
	v_mul_u32_u24_e32 v207, 0x5700, v207
	v_sub_u32_e32 v206, v206, v207
	v_add_u32_e32 v206, s100, v206
	ds_read_u16 v32, v206 offset:128
	s_nop 0
	v_add_u32_e32 v206, s99, v24
	v_mul_hi_u32 v207, v206, s101
	v_mul_u32_u24_e32 v207, 0x5700, v207
	v_sub_u32_e32 v206, v206, v207
	v_add_u32_e32 v206, s100, v206
	ds_read_u16 v33, v206 offset:192
	s_waitcnt lgkmcnt(0)
	v_lshlrev_b32_e32 v24, 16, v96
	v_mul_f32_e32 v24, v26, v24
	v_bfe_u32 v25, v24, 16, 1
	v_add3_u32 v26, v24, v25, s61
	v_mad_i64_i32 v[24:25], s[4:5], v39, s62, v[4:5]
	v_add_u32_e32 v39, 3, v36
	global_store_short_d16_hi v[24:25], v26, off
	v_mad_i64_i32 v[26:27], s[4:5], v39, s57, v[6:7]
	v_lshl_add_u64 v[26:27], v[26:27], 0, s[0:1]
	v_lshl_add_u64 v[28:29], v[26:27], 0, v[2:3]
	v_add_co_u32_e32 v26, vcc, s60, v28
	s_waitcnt lgkmcnt(0)
	v_add_f32_e32 v16, v18, v93
	v_addc_co_u32_e32 v27, vcc, 0, v29, vcc
	v_add_u32_e32 v206, s98, v26
	v_mul_hi_u32 v207, v206, s101
	v_mul_u32_u24_e32 v207, 0x5700, v207
	v_sub_u32_e32 v206, v206, v207
	v_add_u32_e32 v206, s100, v206
	ds_read_u16 v95, v206
	ds_bpermute_b32 v18, v209, v16
	s_waitcnt lgkmcnt(0)
	v_add_f32_e32 v16, v16, v18
	v_fmamk_f32 v16, v16, 0x3c000000, v211
	v_mul_f32_e32 v18, 0x4f800000, v16
	v_cmp_gt_f32_e32 vcc, s58, v16
	s_nop 1
	v_cndmask_b32_e32 v16, v16, v18, vcc
	v_sqrt_f32_e32 v18, v16
	s_nop 0
	v_add_u32_e32 v19, -1, v18
	v_fma_f32 v20, -v19, v18, v16
	v_cmp_ge_f32_e64 s[4:5], 0, v20
	v_add_u32_e32 v20, 1, v18
	s_nop 0
	v_cndmask_b32_e64 v19, v18, v19, s[4:5]
	v_fma_f32 v18, -v20, v18, v16
	v_cmp_lt_f32_e64 s[4:5], 0, v18
	s_nop 1
	v_cndmask_b32_e64 v18, v19, v20, s[4:5]
	v_mul_f32_e32 v19, 0x37800000, v18
	v_cndmask_b32_e32 v18, v18, v19, vcc
	v_cmp_class_f32_e32 vcc, v16, v212
	s_nop 1
	v_mov_b32_dpp v20, v14 quad_perm:[1,0,3,2] row_mask:0xf bank_mask:0xf
	s_waitcnt lgkmcnt(0)
	v_add_f32_e32 v14, v14, v20
	v_cndmask_b32_e32 v16, v18, v16, vcc
	v_div_scale_f32 v18, s[4:5], v16, v16, s59
	v_rcp_f32_e32 v19, v18
	v_div_scale_f32 v20, vcc, s59, v16, s59
	v_fma_f32 v17, -v18, v19, 1.0
	v_fmac_f32_e32 v19, v17, v19
	s_nop 1
	v_mov_b32_dpp v17, v14 quad_perm:[2,3,0,1] row_mask:0xf bank_mask:0xf
	v_mul_f32_e32 v22, v20, v19
	v_fma_f32 v93, -v18, v22, v20
	v_fmac_f32_e32 v22, v93, v19
	v_fma_f32 v18, -v18, v22, v20
	s_waitcnt lgkmcnt(0)
	v_add_f32_e32 v14, v14, v17
	s_nop 1
	v_mov_b32_dpp v17, v14 row_half_mirror row_mask:0xf bank_mask:0xf
	v_div_fmas_f32 v18, v18, v19, v22
	v_div_fixup_f32 v20, v18, v16, s59
	v_mul_f32_e32 v16, v89, v20
	v_mul_f32_e32 v19, v108, v31
	s_waitcnt lgkmcnt(0)
	v_add_f32_e32 v14, v14, v17
	v_mul_f32_e32 v18, v16, v34
	v_lshl_add_u64 v[16:17], v[28:29], 0, s[20:21]
	v_mul_f32_e32 v19, v19, v35
	s_waitcnt lgkmcnt(0)
	v_lshlrev_b32_e32 v28, 16, v94
	v_mul_f32_e32 v19, v19, v28
	v_bfe_u32 v28, v19, 16, 1
	v_add3_u32 v19, v19, v28, s61
	global_store_short_d16_hi v[24:25], v19, off offset:64
	v_mul_f32_e32 v19, v112, v31
	v_mul_f32_e32 v19, v19, v37
	s_waitcnt lgkmcnt(0)
; DI float bf2f(unsigned short u) { return __uint_as_float((unsigned)u << 16); }
; DI unsigned f2bf(float f) { unsigned u = __float_as_uint(f); return (u + 0x7fffu + ((u >> 16) & 1u)) >> 16; }
; DI int crow(int i, int hh) { return (i & 3) + 8 * (i >> 2) + 4 * hh; }
; DI void attn_unit(Ctx A_, LAS unsigned char* lds, int b, int h, int qb, float lam, int wave, int lane) {
;     ...
;         for (int i = 0; i < 16; ++i) {
;             float v = ssq[i];
; #pragma unroll
;             for (int x = 1; x < 32; x <<= 1) v += __shfl_xor(v, x);
;             ssq[i] = ONE_M_LAMINIT / sqrtf(v * (1.0f / 128.0f) + NORM_EPS);
;         }
; #pragma unroll
;         for (int nb = 0; nb < 4; ++nb) {
;             const float sn = SUB_NORM[nb * 32 + r_e];
; #pragma unroll
;             for (int i = 0; i < 16; ++i) {
;                 const size_t rw = (size_t)(rowq_e + crow(i, hh_e));
;                 Y_[rw * YLD + C_YA + h_e * 128 + nb * 32 + r_e] = (bf16)f2bf(o[nb][i] * ssq[i] * sn * bf2f(P[rw * PLD + C_ZA + h_e * 128 + nb * 32 + r_e]));
	v_lshlrev_b32_e32 v28, 16, v32
	v_mul_f32_e32 v19, v19, v28
	v_bfe_u32 v28, v19, 16, 1
	v_add3_u32 v19, v19, v28, s61
	v_add_u32_e32 v206, s99, v16
	v_mul_hi_u32 v207, v206, s101
	v_mul_u32_u24_e32 v207, 0x5700, v207
	v_sub_u32_e32 v206, v206, v207
	v_add_u32_e32 v206, s100, v206
	ds_read_u16 v89, v206 offset:64
	s_waitcnt lgkmcnt(0)
	v_lshlrev_b32_e32 v28, 16, v33
	global_store_short_d16_hi v[24:25], v19, off offset:128
	v_mul_f32_e32 v19, v30, v31
	v_mul_f32_e32 v19, v19, v38
	v_mul_f32_e32 v19, v19, v28
	v_bfe_u32 v28, v19, 16, 1
	v_add3_u32 v19, v19, v28, s61
	global_store_short_d16_hi v[24:25], v19, off offset:192
	ds_read2st64_b32 v[26:27], v64 offset0:8 offset1:9
	v_add_u32_e32 v206, s99, v16
	v_mul_hi_u32 v207, v206, s101
	v_mul_u32_u24_e32 v207, 0x5700, v207
	v_sub_u32_e32 v206, v206, v207
	v_add_u32_e32 v206, s100, v206
	ds_read_u16 v32, v206 offset:128
	v_add_u32_e32 v206, s99, v16
	v_mul_hi_u32 v207, v206, s101
	v_mul_u32_u24_e32 v207, 0x5700, v207
	v_sub_u32_e32 v206, v206, v207
	v_add_u32_e32 v206, s100, v206
	ds_read_u16 v33, v206 offset:192
	s_waitcnt lgkmcnt(0)
	v_lshlrev_b32_e32 v16, 16, v95
	v_mul_f32_e32 v16, v18, v16
	v_bfe_u32 v17, v16, 16, 1
	v_add3_u32 v16, v16, v17, s61
	v_mad_i64_i32 v[28:29], s[4:5], v39, s62, v[4:5]
	v_add_u32_e32 v39, 8, v36
	global_store_short_d16_hi v[28:29], v16, off
	v_mad_i64_i32 v[16:17], s[4:5], v39, s57, v[6:7]
	v_lshl_add_u64 v[16:17], v[16:17], 0, s[0:1]
	v_lshl_add_u64 v[30:31], v[16:17], 0, v[2:3]
	v_add_co_u32_e32 v16, vcc, s60, v30
	s_nop 1
	v_mov_b32_dpp v22, v14 row_mirror row_mask:0xf bank_mask:0xf
	s_nop 0
	v_addc_co_u32_e32 v17, vcc, 0, v31, vcc
	v_add_u32_e32 v206, s98, v16
	v_mul_hi_u32 v207, v206, s101
	v_mul_u32_u24_e32 v207, 0x5700, v207
	v_sub_u32_e32 v206, v206, v207
	v_add_u32_e32 v206, s100, v206
	ds_read_u16 v93, v206
	s_waitcnt lgkmcnt(1)
	v_sub_f32_e32 v26, v78, v26
	s_waitcnt lgkmcnt(0)
	v_add_f32_e32 v14, v14, v22
	ds_bpermute_b32 v22, v209, v14
	v_sub_f32_e32 v78, v79, v15
	v_sub_f32_e32 v79, v80, v21
	v_mul_f32_e32 v15, v78, v78
	v_sub_f32_e32 v80, v81, v23
	s_waitcnt lgkmcnt(0)
	v_add_f32_e32 v14, v14, v22
	v_fmamk_f32 v14, v14, 0x3c000000, v211
	v_mul_f32_e32 v21, 0x4f800000, v14
	v_cmp_gt_f32_e32 vcc, s58, v14
	v_fmac_f32_e32 v15, v83, v83
	v_fmac_f32_e32 v15, v79, v79
	v_cndmask_b32_e32 v14, v14, v21, vcc
	v_sqrt_f32_e32 v21, v14
	v_fmac_f32_e32 v15, v80, v80
	v_sub_f32_e32 v94, v77, v10
	ds_read2st64_b32 v[24:25], v64 offset0:10 offset1:11
	ds_read2st64_b32 v[18:19], v64 offset0:12 offset1:13
	ds_read2st64_b32 v[16:17], v64 offset0:14 offset1:15
	v_add_u32_e32 v22, -1, v21
	v_fma_f32 v23, -v22, v21, v14
	v_cmp_ge_f32_e64 s[4:5], 0, v23
	v_add_u32_e32 v23, 1, v21
	v_mul_f32_e32 v10, v94, v94
	v_cndmask_b32_e64 v22, v21, v22, s[4:5]
	v_fma_f32 v21, -v23, v21, v14
	v_cmp_lt_f32_e64 s[4:5], 0, v21
	v_fmac_f32_e32 v10, v84, v84
	v_sub_f32_e32 v70, v70, v27
	v_cndmask_b32_e64 v21, v22, v23, s[4:5]
	s_nop 1
	v_mov_b32_dpp v23, v15 quad_perm:[1,0,3,2] row_mask:0xf bank_mask:0xf
	v_mul_f32_e32 v22, 0x37800000, v21
	v_cndmask_b32_e32 v21, v21, v22, vcc
	v_cmp_class_f32_e32 vcc, v14, v212
	s_waitcnt lgkmcnt(3)
	v_sub_f32_e32 v24, v69, v24
	s_waitcnt lgkmcnt(0)
	v_add_f32_e32 v15, v15, v23
	v_cndmask_b32_e32 v14, v21, v14, vcc
	v_div_scale_f32 v21, s[4:5], v14, v14, s59
	v_rcp_f32_e32 v22, v21
	s_nop 1
	v_mov_b32_dpp v23, v15 quad_perm:[2,3,0,1] row_mask:0xf bank_mask:0xf
	v_sub_f32_e32 v18, v67, v18
	v_sub_f32_e32 v16, v44, v16
	v_fma_f32 v77, -v21, v22, 1.0
	v_fmac_f32_e32 v22, v77, v22
	v_div_scale_f32 v77, vcc, s59, v14, s59
	s_waitcnt lgkmcnt(0)
	v_add_f32_e32 v15, v15, v23
	v_mul_f32_e32 v81, v77, v22
	s_nop 1
	v_mov_b32_dpp v23, v15 row_half_mirror row_mask:0xf bank_mask:0xf
	v_fma_f32 v95, -v21, v81, v77
	v_fmac_f32_e32 v81, v95, v22
	v_fma_f32 v21, -v21, v81, v77
	v_div_fmas_f32 v21, v21, v22, v81
	v_mul_f32_e32 v22, v90, v20
	s_waitcnt lgkmcnt(0)
	v_add_f32_e32 v81, v15, v23
	v_mul_f32_e32 v22, v22, v35
	s_waitcnt lgkmcnt(0)
	v_lshlrev_b32_e32 v23, 16, v89
	v_mul_f32_e32 v22, v22, v23
	v_bfe_u32 v23, v22, 16, 1
	v_add3_u32 v22, v22, v23, s61
	global_store_short_d16_hi v[28:29], v22, off offset:64
	v_mul_f32_e32 v22, v91, v20
	v_div_fixup_f32 v77, v21, v14, s59
	v_mul_f32_e32 v22, v22, v37
	s_waitcnt lgkmcnt(0)
	v_lshlrev_b32_e32 v23, 16, v32
	v_mul_f32_e32 v14, v88, v77
	v_mul_f32_e32 v22, v22, v23
	v_mul_f32_e32 v21, v14, v34
	v_lshl_add_u64 v[14:15], v[30:31], 0, s[20:21]
	v_bfe_u32 v23, v22, 16, 1
	v_add_u32_e32 v206, s99, v14
	v_mul_hi_u32 v207, v206, s101
	v_mul_u32_u24_e32 v207, 0x5700, v207
	v_sub_u32_e32 v206, v206, v207
	v_add_u32_e32 v206, s100, v206
	ds_read_u16 v30, v206 offset:64
	v_add3_u32 v22, v22, v23, s61
	v_mul_f32_e32 v20, v92, v20
	global_store_short_d16_hi v[28:29], v22, off offset:128
	v_mul_f32_e32 v20, v20, v38
	s_waitcnt lgkmcnt(0)
	v_lshlrev_b32_e32 v22, 16, v33
	v_mul_f32_e32 v20, v20, v22
	v_bfe_u32 v22, v20, 16, 1
	v_add3_u32 v20, v20, v22, s61
	global_store_short_d16_hi v[28:29], v20, off offset:192
	v_add_u32_e32 v206, s99, v14
	v_mul_hi_u32 v207, v206, s101
	v_mul_u32_u24_e32 v207, 0x5700, v207
	v_sub_u32_e32 v206, v206, v207
	v_add_u32_e32 v206, s100, v206
	ds_read_u16 v28, v206 offset:128
	s_nop 0
	v_add_u32_e32 v206, s99, v14
	v_mul_hi_u32 v207, v206, s101
	v_mul_u32_u24_e32 v207, 0x5700, v207
	v_sub_u32_e32 v206, v206, v207
	v_add_u32_e32 v206, s100, v206
	ds_read_u16 v29, v206 offset:192
	s_waitcnt lgkmcnt(0)
; DI float bf2f(unsigned short u) { return __uint_as_float((unsigned)u << 16); }
; DI unsigned f2bf(float f) { unsigned u = __float_as_uint(f); return (u + 0x7fffu + ((u >> 16) & 1u)) >> 16; }
; DI int crow(int i, int hh) { return (i & 3) + 8 * (i >> 2) + 4 * hh; }
; DI void attn_unit(Ctx A_, LAS unsigned char* lds, int b, int h, int qb, float lam, int wave, int lane) {
;     ...
;     if (mp == 0) {
;         float ssq[16];
; #pragma unroll
;         for (int i = 0; i < 16; ++i) ssq[i] = 0.f;
; #pragma unroll
;         for (int nb = 0; nb < 4; ++nb)
; #pragma unroll
;             for (int i = 0; i < 16; ++i) { const float d = o[nb][i] - X2[(nb * 16 + i) * 64]; o[nb][i] = d; ssq[i] += d * d; }
; #pragma unroll
;         for (int i = 0; i < 16; ++i) {
;             float v = ssq[i];
; #pragma unroll
;             for (int x = 1; x < 32; x <<= 1) v += __shfl_xor(v, x);
;             ssq[i] = ONE_M_LAMINIT / sqrtf(v * (1.0f / 128.0f) + NORM_EPS);
;         }
; #pragma unroll
;         for (int nb = 0; nb < 4; ++nb) {
;             const float sn = SUB_NORM[nb * 32 + r_e];
; #pragma unroll
;             for (int i = 0; i < 16; ++i) {
;                 const size_t rw = (size_t)(rowq_e + crow(i, hh_e));
;                 Y_[rw * YLD + C_YA + h_e * 128 + nb * 32 + r_e] = (bf16)f2bf(o[nb][i] * ssq[i] * sn * bf2f(P[rw * PLD + C_ZA + h_e * 128 + nb * 32 + r_e]));
;             }
;         }
;     }
	v_lshlrev_b32_e32 v14, 16, v93
	v_mul_f32_e32 v14, v21, v14
	v_bfe_u32 v15, v14, 16, 1
	v_add3_u32 v20, v14, v15, s61
	v_mad_i64_i32 v[14:15], s[4:5], v39, s62, v[4:5]
	v_add_u32_e32 v31, 9, v36
	s_nop 1
	v_mov_b32_dpp v95, v81 row_mirror row_mask:0xf bank_mask:0xf
	global_store_short_d16_hi v[14:15], v20, off
	v_mad_i64_i32 v[20:21], s[4:5], v31, s57, v[6:7]
	v_lshl_add_u64 v[20:21], v[20:21], 0, s[0:1]
	v_lshl_add_u64 v[20:21], v[20:21], 0, v[2:3]
	v_add_co_u32_e32 v22, vcc, s60, v20
	v_sub_f32_e32 v88, v75, v8
	s_nop 0
	v_addc_co_u32_e32 v23, vcc, 0, v21, vcc
	v_add_u32_e32 v206, s98, v22
	v_mul_hi_u32 v207, v206, s101
	v_mul_u32_u24_e32 v207, 0x5700, v207
	v_sub_u32_e32 v206, v206, v207
	v_add_u32_e32 v206, s100, v206
	ds_read_u16 v22, v206
	s_waitcnt lgkmcnt(0)
	v_add_f32_e32 v23, v81, v95
	ds_bpermute_b32 v32, v209, v23
	v_sub_f32_e32 v39, v74, v11
	v_sub_f32_e32 v89, v76, v12
	v_fmac_f32_e32 v10, v88, v88
	v_fmac_f32_e32 v10, v89, v89
	s_waitcnt lgkmcnt(0)
	v_add_f32_e32 v8, v23, v32
	v_fmamk_f32 v8, v8, 0x3c000000, v211
	v_mul_f32_e32 v11, 0x4f800000, v8
	v_cmp_gt_f32_e32 vcc, s58, v8
	ds_read2st64_b32 v[74:75], v64 offset0:24 offset1:25
	v_mul_f32_e32 v33, v39, v39
	v_cndmask_b32_e32 v8, v8, v11, vcc
	v_sqrt_f32_e32 v11, v8
	v_fmac_f32_e32 v33, v82, v82
	s_waitcnt lgkmcnt(0)
	v_sub_f32_e32 v74, v72, v74
	v_add_u32_e32 v92, 11, v36
	v_add_u32_e32 v12, -1, v11
	v_fma_f32 v23, -v12, v11, v8
	v_cmp_ge_f32_e64 s[4:5], 0, v23
	v_add_u32_e32 v23, 1, v11
	v_sub_f32_e32 v71, v71, v75
	v_cndmask_b32_e64 v12, v11, v12, s[4:5]
	v_fma_f32 v11, -v23, v11, v8
	v_cmp_lt_f32_e64 s[4:5], 0, v11
	v_mul_f32_e32 v75, v71, v71
	v_fmac_f32_e32 v75, v70, v70
	v_cndmask_b32_e64 v11, v12, v23, s[4:5]
	v_mul_f32_e32 v12, 0x37800000, v11
	v_cndmask_b32_e32 v11, v11, v12, vcc
	s_nop 1
	v_mov_b32_dpp v12, v10 quad_perm:[1,0,3,2] row_mask:0xf bank_mask:0xf
	v_cmp_class_f32_e32 vcc, v8, v212
	v_sub_f32_e32 v17, v42, v17
	s_waitcnt lgkmcnt(0)
	v_add_f32_e32 v10, v10, v12
	s_nop 1
	v_mov_b32_dpp v12, v10 quad_perm:[2,3,0,1] row_mask:0xf bank_mask:0xf
	v_cndmask_b32_e32 v8, v11, v8, vcc
	v_div_scale_f32 v11, s[4:5], v8, v8, s59
	v_rcp_f32_e32 v23, v11
	s_waitcnt lgkmcnt(0)
	v_add_f32_e32 v10, v10, v12
	s_nop 1
	v_mov_b32_dpp v12, v10 row_half_mirror row_mask:0xf bank_mask:0xf
	v_fma_f32 v32, -v11, v23, 1.0
	v_fmac_f32_e32 v23, v32, v23
	v_div_scale_f32 v32, vcc, s59, v8, s59
	v_mul_f32_e32 v76, v32, v23
	s_waitcnt lgkmcnt(0)
	v_add_f32_e32 v10, v10, v12
	v_fma_f32 v81, -v11, v76, v32
	s_nop 1
	v_mov_b32_dpp v12, v10 row_mirror row_mask:0xf bank_mask:0xf
	v_fmac_f32_e32 v76, v81, v23
	v_fma_f32 v11, -v11, v76, v32
	v_div_fmas_f32 v11, v11, v23, v76
	v_div_fixup_f32 v32, v11, v8, s59
	s_waitcnt lgkmcnt(0)
	v_add_f32_e32 v8, v10, v12
	v_mul_f32_e32 v10, v83, v32
	v_mul_f32_e32 v23, v10, v34
	v_lshl_add_u64 v[10:11], v[20:21], 0, s[20:21]
	v_mul_f32_e32 v20, v85, v77
	v_mul_f32_e32 v20, v20, v35
	s_waitcnt lgkmcnt(0)
	v_lshlrev_b32_e32 v21, 16, v30
	v_mul_f32_e32 v20, v20, v21
	v_bfe_u32 v21, v20, 16, 1
	v_add3_u32 v20, v20, v21, s61
	global_store_short_d16_hi v[14:15], v20, off offset:64
	v_mul_f32_e32 v20, v86, v77
	v_mul_f32_e32 v20, v20, v37
	s_waitcnt lgkmcnt(0)
	v_lshlrev_b32_e32 v21, 16, v28
	v_mul_f32_e32 v20, v20, v21
	v_bfe_u32 v21, v20, 16, 1
	v_add3_u32 v20, v20, v21, s61
	v_add_u32_e32 v206, s99, v10
	v_mul_hi_u32 v207, v206, s101
	v_mul_u32_u24_e32 v207, 0x5700, v207
	v_sub_u32_e32 v206, v206, v207
	v_add_u32_e32 v206, s100, v206
	ds_read_u16 v30, v206 offset:64
	s_waitcnt lgkmcnt(0)
	v_lshlrev_b32_e32 v21, 16, v29
	global_store_short_d16_hi v[14:15], v20, off offset:128
	v_mul_f32_e32 v20, v87, v77
	v_mul_f32_e32 v20, v20, v38
	v_mul_f32_e32 v20, v20, v21
	v_bfe_u32 v21, v20, 16, 1
	v_add3_u32 v20, v20, v21, s61
	global_store_short_d16_hi v[14:15], v20, off offset:192
	v_add_u32_e32 v206, s99, v10
	v_mul_hi_u32 v207, v206, s101
	v_mul_u32_u24_e32 v207, 0x5700, v207
	v_sub_u32_e32 v206, v206, v207
	v_add_u32_e32 v206, s100, v206
	ds_read_u16 v76, v206 offset:128
	v_add_u32_e32 v206, s99, v10
	v_mul_hi_u32 v207, v206, s101
	v_mul_u32_u24_e32 v207, 0x5700, v207
	v_sub_u32_e32 v206, v206, v207
	v_add_u32_e32 v206, s100, v206
	ds_read_u16 v77, v206 offset:192
	s_waitcnt lgkmcnt(0)
	v_lshlrev_b32_e32 v10, 16, v22
	v_mul_f32_e32 v10, v23, v10
	v_bfe_u32 v11, v10, 16, 1
	v_add3_u32 v10, v10, v11, s61
	v_mad_i64_i32 v[20:21], s[4:5], v31, s62, v[4:5]
	v_add_u32_e32 v31, 10, v36
	ds_bpermute_b32 v12, v209, v8
	global_store_short_d16_hi v[20:21], v10, off
	v_mad_i64_i32 v[10:11], s[4:5], v31, s57, v[6:7]
	v_lshl_add_u64 v[10:11], v[10:11], 0, s[0:1]
	v_lshl_add_u64 v[22:23], v[10:11], 0, v[2:3]
	v_add_co_u32_e32 v10, vcc, s60, v22
	s_waitcnt lgkmcnt(0)
	v_add_f32_e32 v8, v8, v12
	v_addc_co_u32_e32 v11, vcc, 0, v23, vcc
	v_add_u32_e32 v206, s98, v10
	v_mul_hi_u32 v207, v206, s101
	v_mul_u32_u24_e32 v207, 0x5700, v207
	v_sub_u32_e32 v206, v206, v207
	v_add_u32_e32 v206, s100, v206
	ds_read_u16 v81, v206
	v_fmamk_f32 v8, v8, 0x3c000000, v211
	v_sub_f32_e32 v85, v65, v9
	v_mul_f32_e32 v9, 0x4f800000, v8
	v_cmp_gt_f32_e32 vcc, s58, v8
	v_sub_f32_e32 v86, v73, v13
	v_fmac_f32_e32 v33, v85, v85
	v_cndmask_b32_e32 v8, v8, v9, vcc
	v_sqrt_f32_e32 v9, v8
	v_fmac_f32_e32 v33, v86, v86
	ds_read2st64_b32 v[28:29], v64 offset0:26 offset1:27
	ds_read2st64_b32 v[14:15], v64 offset0:28 offset1:29
	ds_read2st64_b32 v[10:11], v64 offset0:30 offset1:31
	ds_read2st64_b32 v[72:73], v64 offset0:40 offset1:41
	v_add_u32_e32 v12, -1, v9
	v_fma_f32 v13, -v12, v9, v8
	v_cmp_ge_f32_e64 s[4:5], 0, v13
	v_add_u32_e32 v13, 1, v9
	s_waitcnt lgkmcnt(0)
; DI float bf2f(unsigned short u) { return __uint_as_float((unsigned)u << 16); }
; DI unsigned f2bf(float f) { unsigned u = __float_as_uint(f); return (u + 0x7fffu + ((u >> 16) & 1u)) >> 16; }
; DI int crow(int i, int hh) { return (i & 3) + 8 * (i >> 2) + 4 * hh; }
; DI void attn_unit(Ctx A_, LAS unsigned char* lds, int b, int h, int qb, float lam, int wave, int lane) {
;     ...
;     if (mp == 0) {
;         float ssq[16];
; #pragma unroll
;         for (int i = 0; i < 16; ++i) ssq[i] = 0.f;
; #pragma unroll
;         for (int nb = 0; nb < 4; ++nb)
; #pragma unroll
;             for (int i = 0; i < 16; ++i) { const float d = o[nb][i] - X2[(nb * 16 + i) * 64]; o[nb][i] = d; ssq[i] += d * d; }
; #pragma unroll
;         for (int i = 0; i < 16; ++i) {
;             float v = ssq[i];
; #pragma unroll
;             for (int x = 1; x < 32; x <<= 1) v += __shfl_xor(v, x);
;             ssq[i] = ONE_M_LAMINIT / sqrtf(v * (1.0f / 128.0f) + NORM_EPS);
;         }
; #pragma unroll
;         for (int nb = 0; nb < 4; ++nb) {
;             const float sn = SUB_NORM[nb * 32 + r_e];
; #pragma unroll
;             for (int i = 0; i < 16; ++i) {
;                 const size_t rw = (size_t)(rowq_e + crow(i, hh_e));
;                 Y_[rw * YLD + C_YA + h_e * 128 + nb * 32 + r_e] = (bf16)f2bf(o[nb][i] * ssq[i] * sn * bf2f(P[rw * PLD + C_ZA + h_e * 128 + nb * 32 + r_e]));
;             }
;         }
;     }
	v_sub_f32_e32 v72, v62, v72
	v_cndmask_b32_e64 v12, v9, v12, s[4:5]
	v_fma_f32 v9, -v13, v9, v8
	v_cmp_lt_f32_e64 s[4:5], 0, v9
	v_mul_f32_e32 v83, v74, v74
	v_fmac_f32_e32 v83, v26, v26
	v_cndmask_b32_e64 v9, v12, v13, s[4:5]
	v_mul_f32_e32 v12, 0x37800000, v9
	v_cndmask_b32_e32 v9, v9, v12, vcc
	s_nop 1
	v_mov_b32_dpp v12, v33 quad_perm:[1,0,3,2] row_mask:0xf bank_mask:0xf
	v_cmp_class_f32_e32 vcc, v8, v212
	v_fmac_f32_e32 v83, v72, v72
	v_sub_f32_e32 v73, v60, v73
	v_cndmask_b32_e32 v8, v9, v8, vcc
	s_waitcnt lgkmcnt(0)
	v_add_f32_e32 v12, v33, v12
	s_nop 1
	v_mov_b32_dpp v33, v12 quad_perm:[2,3,0,1] row_mask:0xf bank_mask:0xf
	v_div_scale_f32 v9, s[4:5], v8, v8, s59
	v_rcp_f32_e32 v13, v9
	v_fmac_f32_e32 v75, v73, v73
	s_waitcnt lgkmcnt(0)
	v_add_f32_e32 v12, v12, v33
	s_nop 1
	v_mov_b32_dpp v33, v12 row_half_mirror row_mask:0xf bank_mask:0xf
	v_fma_f32 v65, -v9, v13, 1.0
	v_fmac_f32_e32 v13, v65, v13
	v_div_scale_f32 v65, vcc, s59, v8, s59
	v_mul_f32_e32 v87, v65, v13
	v_fma_f32 v90, -v9, v87, v65
	s_waitcnt lgkmcnt(0)
	v_add_f32_e32 v12, v12, v33
	v_fmac_f32_e32 v87, v90, v13
	s_nop 1
	v_mov_b32_dpp v33, v12 row_mirror row_mask:0xf bank_mask:0xf
	v_fma_f32 v9, -v9, v87, v65
	v_div_fmas_f32 v9, v9, v13, v87
	v_div_fixup_f32 v65, v9, v8, s59
	v_mul_f32_e32 v8, v84, v65
	v_mul_f32_e32 v13, v78, v32
	s_waitcnt lgkmcnt(0)
	v_add_f32_e32 v33, v12, v33
	v_mul_f32_e32 v12, v8, v34
	v_lshl_add_u64 v[8:9], v[22:23], 0, s[20:21]
	v_mul_f32_e32 v13, v13, v35
	s_waitcnt lgkmcnt(0)
	v_lshlrev_b32_e32 v22, 16, v30
	v_mul_f32_e32 v13, v13, v22
	v_bfe_u32 v22, v13, 16, 1
	v_add3_u32 v13, v13, v22, s61
	global_store_short_d16_hi v[20:21], v13, off offset:64
	v_mul_f32_e32 v13, v79, v32
	v_mul_f32_e32 v13, v13, v37
	s_waitcnt lgkmcnt(0)
	v_lshlrev_b32_e32 v22, 16, v76
	v_mul_f32_e32 v13, v13, v22
	v_bfe_u32 v22, v13, 16, 1
	v_add3_u32 v13, v13, v22, s61
	global_store_short_d16_hi v[20:21], v13, off offset:128
	v_mul_f32_e32 v13, v80, v32
	v_add_u32_e32 v206, s99, v8
	v_mul_hi_u32 v207, v206, s101
	v_mul_u32_u24_e32 v207, 0x5700, v207
	v_sub_u32_e32 v206, v206, v207
	v_add_u32_e32 v206, s100, v206
	ds_read_u16 v84, v206 offset:64
	v_mul_f32_e32 v13, v13, v38
	s_waitcnt lgkmcnt(0)
	v_lshlrev_b32_e32 v22, 16, v77
	v_mul_f32_e32 v13, v13, v22
	v_bfe_u32 v22, v13, 16, 1
	v_add3_u32 v13, v13, v22, s61
	global_store_short_d16_hi v[20:21], v13, off offset:192
	v_add_u32_e32 v206, s99, v8
	v_mul_hi_u32 v207, v206, s101
	v_mul_u32_u24_e32 v207, 0x5700, v207
	v_sub_u32_e32 v206, v206, v207
	v_add_u32_e32 v206, s100, v206
	ds_read_u16 v90, v206 offset:128
	v_add_u32_e32 v206, s99, v8
	v_mul_hi_u32 v207, v206, s101
	v_mul_u32_u24_e32 v207, 0x5700, v207
	v_sub_u32_e32 v206, v206, v207
	v_add_u32_e32 v206, s100, v206
	ds_read_u16 v91, v206 offset:192
	v_mad_i64_i32 v[76:77], s[4:5], v31, s62, v[4:5]
	ds_bpermute_b32 v87, v209, v33
	s_waitcnt lgkmcnt(0)
	v_lshlrev_b32_e32 v8, 16, v81
	v_mul_f32_e32 v8, v12, v8
	v_bfe_u32 v9, v8, 16, 1
	v_add3_u32 v8, v8, v9, s61
	global_store_short_d16_hi v[76:77], v8, off
	v_mad_i64_i32 v[8:9], s[4:5], v92, s57, v[6:7]
	v_lshl_add_u64 v[8:9], v[8:9], 0, s[0:1]
	v_lshl_add_u64 v[78:79], v[8:9], 0, v[2:3]
	v_add_co_u32_e32 v8, vcc, s60, v78
	v_sub_f32_e32 v57, v57, v28
	s_nop 0
	v_addc_co_u32_e32 v9, vcc, 0, v79, vcc
	v_add_u32_e32 v206, s98, v8
	v_mul_hi_u32 v207, v206, s101
	v_mul_u32_u24_e32 v207, 0x5700, v207
	v_sub_u32_e32 v206, v206, v207
	v_add_u32_e32 v206, s100, v206
	ds_read_u16 v93, v206
	s_waitcnt lgkmcnt(0)
	v_add_f32_e32 v8, v33, v87
	v_fmamk_f32 v8, v8, 0x3c000000, v211
	v_mul_f32_e32 v9, 0x4f800000, v8
	v_cmp_gt_f32_e32 vcc, s58, v8
	ds_read2st64_b32 v[30:31], v64 offset0:42 offset1:43
	ds_read2st64_b32 v[20:21], v64 offset0:44 offset1:45
	ds_read2st64_b32 v[12:13], v64 offset0:46 offset1:47
	ds_read2st64_b32 v[80:81], v64 offset0:56 offset1:57
	v_cndmask_b32_e32 v62, v8, v9, vcc
	v_sqrt_f32_e32 v87, v62
	ds_read2st64_b32 v[32:33], v64 offset0:58 offset1:59
	ds_read2st64_b32 v[22:23], v64 offset0:60 offset1:61
	ds_read2st64_b32 v[8:9], v64 offset0:62 offset1:63
	s_waitcnt lgkmcnt(6)
	v_sub_f32_e32 v30, v58, v30
	s_waitcnt lgkmcnt(3)
	v_sub_f32_e32 v80, v63, v80
	v_add_u32_e32 v63, -1, v87
	v_fma_f32 v64, -v63, v87, v62
	v_cmp_ge_f32_e64 s[4:5], 0, v64
	v_add_u32_e32 v64, 1, v87
	v_fmac_f32_e32 v83, v80, v80
	v_cndmask_b32_e64 v63, v87, v63, s[4:5]
	v_fma_f32 v87, -v64, v87, v62
	v_cmp_lt_f32_e64 s[4:5], 0, v87
	s_nop 1
	v_mov_b32_dpp v87, v83 quad_perm:[1,0,3,2] row_mask:0xf bank_mask:0xf
	s_waitcnt lgkmcnt(3)
	v_sub_f32_e32 v32, v59, v32
	v_cndmask_b32_e64 v63, v63, v64, s[4:5]
	v_mul_f32_e32 v64, 0x37800000, v63
	v_cndmask_b32_e32 v63, v63, v64, vcc
	v_cmp_class_f32_e32 vcc, v62, v212
	s_waitcnt lgkmcnt(0)
	v_add_f32_e32 v83, v83, v87
	s_nop 1
	v_mov_b32_dpp v87, v83 quad_perm:[2,3,0,1] row_mask:0xf bank_mask:0xf
	v_cndmask_b32_e32 v62, v63, v62, vcc
	v_div_scale_f32 v63, s[4:5], v62, v62, s59
	v_rcp_f32_e32 v64, v63
	s_waitcnt lgkmcnt(0)
	v_add_f32_e32 v83, v83, v87
	s_nop 1
	v_mov_b32_dpp v87, v83 row_half_mirror row_mask:0xf bank_mask:0xf
	v_mul_f32_e32 v28, v57, v57
	v_fma_f32 v95, -v63, v64, 1.0
	v_fmac_f32_e32 v64, v95, v64
	v_div_scale_f32 v95, vcc, s59, v62, s59
	v_mul_f32_e32 v96, v95, v64
	v_fma_f32 v97, -v63, v96, v95
	v_fmac_f32_e32 v96, v97, v64
	v_fma_f32 v63, -v63, v96, v95
	v_div_fmas_f32 v63, v63, v64, v96
	v_div_fixup_f32 v95, v63, v62, s59
	v_mul_f32_e32 v62, v82, v95
	v_mul_f32_e32 v64, v62, v34
	v_lshl_add_u64 v[62:63], v[78:79], 0, s[20:21]
	v_mul_f32_e32 v78, v94, v65
	v_mul_f32_e32 v78, v78, v35
	s_waitcnt lgkmcnt(0)
; DI float bf2f(unsigned short u) { return __uint_as_float((unsigned)u << 16); }
; DI unsigned f2bf(float f) { unsigned u = __float_as_uint(f); return (u + 0x7fffu + ((u >> 16) & 1u)) >> 16; }
; DI int crow(int i, int hh) { return (i & 3) + 8 * (i >> 2) + 4 * hh; }
; DI void attn_unit(Ctx A_, LAS unsigned char* lds, int b, int h, int qb, float lam, int wave, int lane) {
;     ...
;     if (mp == 0) {
;         float ssq[16];
; #pragma unroll
;         for (int i = 0; i < 16; ++i) ssq[i] = 0.f;
; #pragma unroll
;         for (int nb = 0; nb < 4; ++nb)
; #pragma unroll
;             for (int i = 0; i < 16; ++i) { const float d = o[nb][i] - X2[(nb * 16 + i) * 64]; o[nb][i] = d; ssq[i] += d * d; }
; #pragma unroll
;         for (int i = 0; i < 16; ++i) {
;             float v = ssq[i];
; #pragma unroll
;             for (int x = 1; x < 32; x <<= 1) v += __shfl_xor(v, x);
;             ssq[i] = ONE_M_LAMINIT / sqrtf(v * (1.0f / 128.0f) + NORM_EPS);
;         }
; #pragma unroll
;         for (int nb = 0; nb < 4; ++nb) {
;             const float sn = SUB_NORM[nb * 32 + r_e];
; #pragma unroll
;             for (int i = 0; i < 16; ++i) {
;                 const size_t rw = (size_t)(rowq_e + crow(i, hh_e));
;                 Y_[rw * YLD + C_YA + h_e * 128 + nb * 32 + r_e] = (bf16)f2bf(o[nb][i] * ssq[i] * sn * bf2f(P[rw * PLD + C_ZA + h_e * 128 + nb * 32 + r_e]));
;             }
;         }
;     }
	v_add_f32_e32 v83, v83, v87
	s_nop 1
	v_mov_b32_dpp v87, v83 row_mirror row_mask:0xf bank_mask:0xf
	v_mul_f32_e32 v39, v39, v95
	v_mul_f32_e32 v39, v39, v35
	v_fmac_f32_e32 v28, v24, v24
	s_waitcnt lgkmcnt(0)
	v_lshlrev_b32_e32 v79, 16, v84
	v_mul_f32_e32 v78, v78, v79
	v_bfe_u32 v79, v78, 16, 1
	v_add3_u32 v78, v78, v79, s61
	v_mul_f32_e32 v79, v88, v65
	v_mul_f32_e32 v79, v79, v37
	s_waitcnt lgkmcnt(0)
	v_lshlrev_b32_e32 v82, 16, v90
	v_mul_f32_e32 v79, v79, v82
	v_bfe_u32 v82, v79, 16, 1
	global_store_short_d16_hi v[76:77], v78, off offset:64
	v_add3_u32 v79, v79, v82, s61
	v_mul_f32_e32 v65, v89, v65
	v_add_u32_e32 v206, s99, v62
	v_mul_hi_u32 v207, v206, s101
	v_mul_u32_u24_e32 v207, 0x5700, v207
	v_sub_u32_e32 v206, v206, v207
	v_add_u32_e32 v206, s100, v206
	ds_read_u16 v78, v206 offset:64
	v_mul_f32_e32 v65, v65, v38
	global_store_short_d16_hi v[76:77], v79, off offset:128
	s_waitcnt lgkmcnt(0)
	v_lshlrev_b32_e32 v79, 16, v91
	v_mul_f32_e32 v65, v65, v79
	v_bfe_u32 v79, v65, 16, 1
	v_add3_u32 v65, v65, v79, s61
	global_store_short_d16_hi v[76:77], v65, off offset:192
	v_add_u32_e32 v206, s99, v62
	v_mul_hi_u32 v207, v206, s101
	v_mul_u32_u24_e32 v207, 0x5700, v207
	v_sub_u32_e32 v206, v206, v207
	v_add_u32_e32 v206, s100, v206
	ds_read_u16 v79, v206 offset:128
	v_add_u32_e32 v206, s99, v62
	v_mul_hi_u32 v207, v206, s101
	v_mul_u32_u24_e32 v207, 0x5700, v207
	v_sub_u32_e32 v206, v206, v207
	v_add_u32_e32 v206, s100, v206
	ds_read_u16 v82, v206 offset:192
	v_add_u32_e32 v84, 16, v36
	s_waitcnt lgkmcnt(0)
	v_add_f32_e32 v27, v83, v87
	v_fmac_f32_e32 v28, v30, v30
	v_fmac_f32_e32 v28, v32, v32
	s_waitcnt lgkmcnt(0)
	v_lshlrev_b32_e32 v62, 16, v93
	v_mul_f32_e32 v62, v64, v62
	v_bfe_u32 v63, v62, 16, 1
	v_add3_u32 v64, v62, v63, s61
	v_mad_i64_i32 v[62:63], s[4:5], v92, s62, v[4:5]
	global_store_short_d16_hi v[62:63], v64, off
	v_mad_i64_i32 v[64:65], s[4:5], v84, s57, v[6:7]
	v_lshl_add_u64 v[64:65], v[64:65], 0, s[0:1]
	v_lshl_add_u64 v[64:65], v[64:65], 0, v[2:3]
	v_add_co_u32_e32 v76, vcc, s60, v64
	v_sub_f32_e32 v54, v54, v29
	s_nop 0
	v_addc_co_u32_e32 v77, vcc, 0, v65, vcc
	v_add_u32_e32 v206, s98, v76
	v_mul_hi_u32 v207, v206, s101
	v_mul_u32_u24_e32 v207, 0x5700, v207
	v_sub_u32_e32 v206, v206, v207
	v_add_u32_e32 v206, s100, v206
	ds_read_u16 v76, v206
	ds_bpermute_b32 v77, v209, v27
	v_sub_f32_e32 v31, v55, v31
	v_mul_f32_e32 v29, v54, v54
	v_sub_f32_e32 v33, v56, v33
	v_sub_f32_e32 v51, v51, v14
	s_waitcnt lgkmcnt(0)
	v_add_f32_e32 v27, v27, v77
	v_fmamk_f32 v27, v27, 0x3c000000, v211
	v_mul_f32_e32 v60, 0x4f800000, v27
	v_cmp_gt_f32_e32 vcc, s58, v27
	v_sub_f32_e32 v77, v61, v81
	v_fmac_f32_e32 v75, v77, v77
	v_cndmask_b32_e32 v27, v27, v60, vcc
	v_sqrt_f32_e32 v60, v27
	v_sub_f32_e32 v52, v52, v20
	v_sub_f32_e32 v22, v53, v22
	v_sub_f32_e32 v48, v48, v15
	v_add_u32_e32 v61, -1, v60
	v_fma_f32 v81, -v61, v60, v27
	v_cmp_ge_f32_e64 s[4:5], 0, v81
	v_add_u32_e32 v81, 1, v60
	v_sub_f32_e32 v49, v49, v21
	v_cndmask_b32_e64 v61, v60, v61, s[4:5]
	v_fma_f32 v60, -v81, v60, v27
	v_cmp_lt_f32_e64 s[4:5], 0, v60
	v_sub_f32_e32 v23, v50, v23
	v_sub_f32_e32 v12, v46, v12
	v_cndmask_b32_e64 v60, v61, v81, s[4:5]
	v_mul_f32_e32 v61, 0x37800000, v60
	v_cndmask_b32_e32 v60, v60, v61, vcc
	v_cmp_class_f32_e32 vcc, v27, v212
	s_nop 1
	v_mov_b32_dpp v81, v75 quad_perm:[1,0,3,2] row_mask:0xf bank_mask:0xf
	v_sub_f32_e32 v13, v40, v13
	v_cndmask_b32_e32 v27, v60, v27, vcc
	v_div_scale_f32 v60, s[4:5], v27, v27, s59
	v_rcp_f32_e32 v61, v60
	s_waitcnt lgkmcnt(0)
	v_add_f32_e32 v75, v75, v81
	s_nop 1
	v_mov_b32_dpp v81, v75 quad_perm:[2,3,0,1] row_mask:0xf bank_mask:0xf
	v_fma_f32 v83, -v60, v61, 1.0
	v_fmac_f32_e32 v61, v83, v61
	v_div_scale_f32 v83, vcc, s59, v27, s59
	v_mul_f32_e32 v87, v83, v61
	v_fma_f32 v88, -v60, v87, v83
	v_fmac_f32_e32 v87, v88, v61
	v_fma_f32 v60, -v60, v87, v83
	v_div_fmas_f32 v60, v60, v61, v87
	v_div_fixup_f32 v83, v60, v27, s59
	v_mul_f32_e32 v26, v26, v83
	s_waitcnt lgkmcnt(0)
	v_lshlrev_b32_e32 v61, 16, v78
	v_mul_f32_e32 v39, v39, v61
	v_bfe_u32 v61, v39, 16, 1
	v_add3_u32 v39, v39, v61, s61
	v_mul_f32_e32 v61, v85, v95
	v_mul_f32_e32 v60, v26, v34
	v_lshl_add_u64 v[26:27], v[64:65], 0, s[20:21]
	v_mul_f32_e32 v61, v61, v37
	s_waitcnt lgkmcnt(0)
	v_lshlrev_b32_e32 v64, 16, v79
	v_mul_f32_e32 v61, v61, v64
	v_bfe_u32 v64, v61, 16, 1
	v_add3_u32 v61, v61, v64, s61
	global_store_short_d16_hi v[62:63], v39, off offset:64
	global_store_short_d16_hi v[62:63], v61, off offset:128
	v_mul_f32_e32 v61, v86, v95
	v_add_u32_e32 v206, s99, v26
	v_mul_hi_u32 v207, v206, s101
	v_mul_u32_u24_e32 v207, 0x5700, v207
	v_sub_u32_e32 v206, v206, v207
	v_add_u32_e32 v206, s100, v206
	ds_read_u16 v39, v206 offset:64
	v_mul_f32_e32 v61, v61, v38
	s_waitcnt lgkmcnt(0)
	v_lshlrev_b32_e32 v64, 16, v82
	v_mul_f32_e32 v61, v61, v64
	v_bfe_u32 v64, v61, 16, 1
	v_add3_u32 v61, v61, v64, s61
	global_store_short_d16_hi v[62:63], v61, off offset:192
	v_add_u32_e32 v206, s99, v26
	v_mul_hi_u32 v207, v206, s101
	v_mul_u32_u24_e32 v207, 0x5700, v207
	v_sub_u32_e32 v206, v206, v207
	v_add_u32_e32 v206, s100, v206
	ds_read_u16 v64, v206 offset:128
	v_add_u32_e32 v206, s99, v26
	v_mul_hi_u32 v207, v206, s101
	v_mul_u32_u24_e32 v207, 0x5700, v207
	v_sub_u32_e32 v206, v206, v207
	v_add_u32_e32 v206, s100, v206
	ds_read_u16 v65, v206 offset:192
	s_waitcnt lgkmcnt(0)
	v_add_f32_e32 v75, v75, v81
	s_nop 1
	v_mov_b32_dpp v81, v75 row_half_mirror row_mask:0xf bank_mask:0xf
	s_waitcnt lgkmcnt(0)
	v_lshlrev_b32_e32 v26, 16, v76
	v_mul_f32_e32 v26, v60, v26
	v_bfe_u32 v27, v26, 16, 1
	s_waitcnt lgkmcnt(0)
; DI float bf2f(unsigned short u) { return __uint_as_float((unsigned)u << 16); }
; DI unsigned f2bf(float f) { unsigned u = __float_as_uint(f); return (u + 0x7fffu + ((u >> 16) & 1u)) >> 16; }
; DI int crow(int i, int hh) { return (i & 3) + 8 * (i >> 2) + 4 * hh; }
; DI void attn_unit(Ctx A_, LAS unsigned char* lds, int b, int h, int qb, float lam, int wave, int lane) {
;     ...
;     if (mp == 0) {
;         float ssq[16];
; #pragma unroll
;         for (int i = 0; i < 16; ++i) ssq[i] = 0.f;
; #pragma unroll
;         for (int nb = 0; nb < 4; ++nb)
; #pragma unroll
;             for (int i = 0; i < 16; ++i) { const float d = o[nb][i] - X2[(nb * 16 + i) * 64]; o[nb][i] = d; ssq[i] += d * d; }
; #pragma unroll
;         for (int i = 0; i < 16; ++i) {
;             float v = ssq[i];
; #pragma unroll
;             for (int x = 1; x < 32; x <<= 1) v += __shfl_xor(v, x);
;             ssq[i] = ONE_M_LAMINIT / sqrtf(v * (1.0f / 128.0f) + NORM_EPS);
;         }
; #pragma unroll
;         for (int nb = 0; nb < 4; ++nb) {
;             const float sn = SUB_NORM[nb * 32 + r_e];
; #pragma unroll
;             for (int i = 0; i < 16; ++i) {
;                 const size_t rw = (size_t)(rowq_e + crow(i, hh_e));
;                 Y_[rw * YLD + C_YA + h_e * 128 + nb * 32 + r_e] = (bf16)f2bf(o[nb][i] * ssq[i] * sn * bf2f(P[rw * PLD + C_ZA + h_e * 128 + nb * 32 + r_e]));
;             }
;         }
;     }
	v_add_f32_e32 v75, v75, v81
	v_add3_u32 v60, v26, v27, s61
	v_mad_i64_i32 v[26:27], s[4:5], v84, s62, v[4:5]
	v_add_u32_e32 v76, 17, v36
	s_nop 1
	v_mov_b32_dpp v81, v75 row_mirror row_mask:0xf bank_mask:0xf
	global_store_short_d16_hi v[26:27], v60, off
	v_mad_i64_i32 v[60:61], s[4:5], v76, s57, v[6:7]
	v_lshl_add_u64 v[60:61], v[60:61], 0, s[0:1]
	v_lshl_add_u64 v[60:61], v[60:61], 0, v[2:3]
	v_add_co_u32_e32 v62, vcc, s60, v60
	s_waitcnt lgkmcnt(0)
	v_lshlrev_b32_e32 v39, 16, v39
	v_addc_co_u32_e32 v63, vcc, 0, v61, vcc
	v_add_u32_e32 v206, s98, v62
	v_mul_hi_u32 v207, v206, s101
	v_mul_u32_u24_e32 v207, 0x5700, v207
	v_sub_u32_e32 v206, v206, v207
	v_add_u32_e32 v206, s100, v206
	ds_read_u16 v62, v206
	s_waitcnt lgkmcnt(0)
	v_add_f32_e32 v63, v75, v81
	ds_bpermute_b32 v69, v209, v63
	s_waitcnt lgkmcnt(0)
	v_add_f32_e32 v58, v63, v69
	v_fmamk_f32 v58, v58, 0x3c000000, v211
	v_mul_f32_e32 v63, 0x4f800000, v58
	v_cmp_gt_f32_e32 vcc, s58, v58
	s_nop 1
	v_cndmask_b32_e32 v58, v58, v63, vcc
	v_sqrt_f32_e32 v63, v58
	s_nop 0
	v_add_u32_e32 v59, -1, v63
	v_fma_f32 v69, -v59, v63, v58
	v_cmp_ge_f32_e64 s[4:5], 0, v69
	v_add_u32_e32 v69, 1, v63
	s_nop 0
	v_cndmask_b32_e64 v59, v63, v59, s[4:5]
	v_fma_f32 v63, -v69, v63, v58
	v_cmp_lt_f32_e64 s[4:5], 0, v63
	s_nop 1
	v_cndmask_b32_e64 v59, v59, v69, s[4:5]
	v_mul_f32_e32 v63, 0x37800000, v59
	v_cndmask_b32_e32 v59, v59, v63, vcc
	v_cmp_class_f32_e32 vcc, v58, v212
	s_nop 1
	v_mov_b32_dpp v69, v28 quad_perm:[1,0,3,2] row_mask:0xf bank_mask:0xf
	s_waitcnt lgkmcnt(0)
	v_add_f32_e32 v28, v28, v69
	v_cndmask_b32_e32 v58, v59, v58, vcc
	v_div_scale_f32 v59, s[4:5], v58, v58, s59
	v_rcp_f32_e32 v63, v59
	s_nop 1
	v_mov_b32_dpp v69, v28 quad_perm:[2,3,0,1] row_mask:0xf bank_mask:0xf
	v_fma_f32 v75, -v59, v63, 1.0
	v_fmac_f32_e32 v63, v75, v63
	v_div_scale_f32 v75, vcc, s59, v58, s59
	v_mul_f32_e32 v78, v75, v63
	v_fma_f32 v79, -v59, v78, v75
	v_fmac_f32_e32 v78, v79, v63
	v_fma_f32 v59, -v59, v78, v75
	v_div_fmas_f32 v59, v59, v63, v78
	v_div_fixup_f32 v63, v59, v58, s59
	v_mul_f32_e32 v58, v70, v63
	v_mul_f32_e32 v70, v58, v34
	v_lshl_add_u64 v[58:59], v[60:61], 0, s[20:21]
	v_mul_f32_e32 v60, v74, v83
	v_mul_f32_e32 v60, v60, v35
	v_mul_f32_e32 v39, v60, v39
	v_bfe_u32 v60, v39, 16, 1
	v_add3_u32 v39, v39, v60, s61
	v_mul_f32_e32 v60, v72, v83
	v_mul_f32_e32 v60, v60, v37
	s_waitcnt lgkmcnt(0)
	v_lshlrev_b32_e32 v61, 16, v64
	v_mul_f32_e32 v60, v60, v61
	v_bfe_u32 v61, v60, 16, 1
	global_store_short_d16_hi v[26:27], v39, off offset:64
	v_add3_u32 v60, v60, v61, s61
	v_add_u32_e32 v206, s99, v58
	v_mul_hi_u32 v207, v206, s101
	v_mul_u32_u24_e32 v207, 0x5700, v207
	v_sub_u32_e32 v206, v206, v207
	v_add_u32_e32 v206, s100, v206
	ds_read_u16 v39, v206 offset:64
	s_waitcnt lgkmcnt(0)
	v_lshlrev_b32_e32 v61, 16, v65
	global_store_short_d16_hi v[26:27], v60, off offset:128
	v_mul_f32_e32 v60, v80, v83
	v_mul_f32_e32 v60, v60, v38
	v_mul_f32_e32 v60, v60, v61
	v_bfe_u32 v61, v60, 16, 1
	v_add3_u32 v60, v60, v61, s61
	global_store_short_d16_hi v[26:27], v60, off offset:192
	v_add_u32_e32 v206, s99, v58
	v_mul_hi_u32 v207, v206, s101
	v_mul_u32_u24_e32 v207, 0x5700, v207
	v_sub_u32_e32 v206, v206, v207
	v_add_u32_e32 v206, s100, v206
	ds_read_u16 v64, v206 offset:128
	v_add_u32_e32 v206, s99, v58
	v_mul_hi_u32 v207, v206, s101
	v_mul_u32_u24_e32 v207, 0x5700, v207
	v_sub_u32_e32 v206, v206, v207
	v_add_u32_e32 v206, s100, v206
	ds_read_u16 v65, v206 offset:192
	s_waitcnt lgkmcnt(0)
	v_add_f32_e32 v28, v28, v69
	s_nop 1
	v_mov_b32_dpp v69, v28 row_half_mirror row_mask:0xf bank_mask:0xf
	s_waitcnt lgkmcnt(0)
	v_lshlrev_b32_e32 v26, 16, v62
	v_mul_f32_e32 v26, v70, v26
	v_bfe_u32 v27, v26, 16, 1
	v_add3_u32 v58, v26, v27, s61
	s_waitcnt lgkmcnt(0)
	v_add_f32_e32 v28, v28, v69
	v_mad_i64_i32 v[26:27], s[4:5], v76, s62, v[4:5]
	v_add_u32_e32 v62, 18, v36
	s_nop 1
	v_mov_b32_dpp v69, v28 row_mirror row_mask:0xf bank_mask:0xf
	global_store_short_d16_hi v[26:27], v58, off
	v_mad_i64_i32 v[58:59], s[4:5], v62, s57, v[6:7]
	v_lshl_add_u64 v[58:59], v[58:59], 0, s[0:1]
	v_lshl_add_u64 v[58:59], v[58:59], 0, v[2:3]
	v_add_co_u32_e32 v60, vcc, s60, v58
	s_waitcnt lgkmcnt(0)
	v_lshlrev_b32_e32 v39, 16, v39
	v_addc_co_u32_e32 v61, vcc, 0, v59, vcc
	v_add_u32_e32 v206, s98, v60
	v_mul_hi_u32 v207, v206, s101
	v_mul_u32_u24_e32 v207, 0x5700, v207
	v_sub_u32_e32 v206, v206, v207
	v_add_u32_e32 v206, s100, v206
	ds_read_u16 v60, v206
	v_sub_f32_e32 v61, v68, v25
	s_waitcnt lgkmcnt(0)
	v_add_f32_e32 v25, v28, v69
	ds_bpermute_b32 v28, v209, v25
	v_fmac_f32_e32 v29, v61, v61
	v_fmac_f32_e32 v29, v31, v31
	v_fmac_f32_e32 v29, v33, v33
	s_waitcnt lgkmcnt(0)
	v_add_f32_e32 v25, v25, v28
	v_fmamk_f32 v25, v25, 0x3c000000, v211
	v_mul_f32_e32 v28, 0x4f800000, v25
	v_cmp_gt_f32_e32 vcc, s58, v25
	s_nop 1
	v_cndmask_b32_e32 v25, v25, v28, vcc
	v_sqrt_f32_e32 v28, v25
	s_nop 0
	v_add_u32_e32 v55, -1, v28
	v_fma_f32 v56, -v55, v28, v25
	v_cmp_ge_f32_e64 s[4:5], 0, v56
	v_add_u32_e32 v56, 1, v28
	s_nop 0
	v_cndmask_b32_e64 v55, v28, v55, s[4:5]
	v_fma_f32 v28, -v56, v28, v25
	v_cmp_lt_f32_e64 s[4:5], 0, v28
	s_nop 1
	v_cndmask_b32_e64 v28, v55, v56, s[4:5]
	s_nop 1
	v_mov_b32_dpp v56, v29 quad_perm:[1,0,3,2] row_mask:0xf bank_mask:0xf
	v_mul_f32_e32 v55, 0x37800000, v28
	v_cndmask_b32_e32 v28, v28, v55, vcc
	v_cmp_class_f32_e32 vcc, v25, v212
	s_waitcnt lgkmcnt(0)
	v_add_f32_e32 v29, v29, v56
	s_nop 1
	v_mov_b32_dpp v56, v29 quad_perm:[2,3,0,1] row_mask:0xf bank_mask:0xf
	v_cndmask_b32_e32 v25, v28, v25, vcc
	v_div_scale_f32 v28, s[4:5], v25, v25, s59
	v_rcp_f32_e32 v55, v28
	s_waitcnt lgkmcnt(0)
; DI float bf2f(unsigned short u) { return __uint_as_float((unsigned)u << 16); }
; DI unsigned f2bf(float f) { unsigned u = __float_as_uint(f); return (u + 0x7fffu + ((u >> 16) & 1u)) >> 16; }
; DI int crow(int i, int hh) { return (i & 3) + 8 * (i >> 2) + 4 * hh; }
; DI void attn_unit(Ctx A_, LAS unsigned char* lds, int b, int h, int qb, float lam, int wave, int lane) {
;     ...
;     if (mp == 0) {
;         float ssq[16];
; #pragma unroll
;         for (int i = 0; i < 16; ++i) ssq[i] = 0.f;
; #pragma unroll
;         for (int nb = 0; nb < 4; ++nb)
; #pragma unroll
;             for (int i = 0; i < 16; ++i) { const float d = o[nb][i] - X2[(nb * 16 + i) * 64]; o[nb][i] = d; ssq[i] += d * d; }
; #pragma unroll
;         for (int i = 0; i < 16; ++i) {
;             float v = ssq[i];
; #pragma unroll
;             for (int x = 1; x < 32; x <<= 1) v += __shfl_xor(v, x);
;             ssq[i] = ONE_M_LAMINIT / sqrtf(v * (1.0f / 128.0f) + NORM_EPS);
;         }
; #pragma unroll
;         for (int nb = 0; nb < 4; ++nb) {
;             const float sn = SUB_NORM[nb * 32 + r_e];
; #pragma unroll
;             for (int i = 0; i < 16; ++i) {
;                 const size_t rw = (size_t)(rowq_e + crow(i, hh_e));
;                 Y_[rw * YLD + C_YA + h_e * 128 + nb * 32 + r_e] = (bf16)f2bf(o[nb][i] * ssq[i] * sn * bf2f(P[rw * PLD + C_ZA + h_e * 128 + nb * 32 + r_e]));
;             }
;         }
;     }
	v_add_f32_e32 v29, v29, v56
	s_nop 1
	v_mov_b32_dpp v56, v29 row_half_mirror row_mask:0xf bank_mask:0xf
	v_fma_f32 v68, -v28, v55, 1.0
	v_fmac_f32_e32 v55, v68, v55
	v_div_scale_f32 v68, vcc, s59, v25, s59
	v_mul_f32_e32 v69, v68, v55
	v_fma_f32 v70, -v28, v69, v68
	s_waitcnt lgkmcnt(0)
	v_add_f32_e32 v56, v29, v56
	v_mul_f32_e32 v29, v71, v63
	v_fmac_f32_e32 v69, v70, v55
	v_mul_f32_e32 v29, v29, v35
	v_fma_f32 v28, -v28, v69, v68
	v_mul_f32_e32 v29, v29, v39
	v_div_fmas_f32 v28, v28, v55, v69
	v_bfe_u32 v39, v29, 16, 1
	v_div_fixup_f32 v55, v28, v25, s59
	v_add3_u32 v29, v29, v39, s61
	v_mul_f32_e32 v24, v24, v55
	global_store_short_d16_hi v[26:27], v29, off offset:64
	v_mul_f32_e32 v29, v73, v63
	v_mul_f32_e32 v28, v24, v34
	v_lshl_add_u64 v[24:25], v[58:59], 0, s[20:21]
	v_mul_f32_e32 v29, v29, v37
	s_waitcnt lgkmcnt(0)
	v_lshlrev_b32_e32 v58, 16, v64
	v_mul_f32_e32 v29, v29, v58
	v_bfe_u32 v58, v29, 16, 1
	v_add3_u32 v29, v29, v58, s61
	global_store_short_d16_hi v[26:27], v29, off offset:128
	v_mul_f32_e32 v29, v77, v63
	v_mul_f32_e32 v29, v29, v38
	s_waitcnt lgkmcnt(0)
	v_lshlrev_b32_e32 v59, 16, v65
	v_mul_f32_e32 v29, v29, v59
	v_add_u32_e32 v206, s99, v24
	v_mul_hi_u32 v207, v206, s101
	v_mul_u32_u24_e32 v207, 0x5700, v207
	v_sub_u32_e32 v206, v206, v207
	v_add_u32_e32 v206, s100, v206
	ds_read_u16 v39, v206 offset:64
	v_add_u32_e32 v206, s99, v24
	v_mul_hi_u32 v207, v206, s101
	v_mul_u32_u24_e32 v207, 0x5700, v207
	v_sub_u32_e32 v206, v206, v207
	v_add_u32_e32 v206, s100, v206
	ds_read_u16 v58, v206 offset:128
	v_bfe_u32 v59, v29, 16, 1
	v_add3_u32 v29, v29, v59, s61
	global_store_short_d16_hi v[26:27], v29, off offset:192
	v_add_u32_e32 v206, s99, v24
	v_mul_hi_u32 v207, v206, s101
	v_mul_u32_u24_e32 v207, 0x5700, v207
	v_sub_u32_e32 v206, v206, v207
	v_add_u32_e32 v206, s100, v206
	ds_read_u16 v59, v206 offset:192
	s_waitcnt lgkmcnt(0)
	v_lshlrev_b32_e32 v24, 16, v60
	v_mul_f32_e32 v24, v28, v24
	v_bfe_u32 v25, v24, 16, 1
	v_add3_u32 v26, v24, v25, s61
	v_mad_i64_i32 v[24:25], s[4:5], v62, s62, v[4:5]
	v_add_u32_e32 v60, 19, v36
	global_store_short_d16_hi v[24:25], v26, off
	v_mad_i64_i32 v[26:27], s[4:5], v60, s57, v[6:7]
	v_lshl_add_u64 v[26:27], v[26:27], 0, s[0:1]
	v_lshl_add_u64 v[26:27], v[26:27], 0, v[2:3]
	v_add_co_u32_e32 v28, vcc, s60, v26
	v_mul_f32_e32 v57, v57, v55
	s_nop 0
	v_addc_co_u32_e32 v29, vcc, 0, v27, vcc
	v_add_u32_e32 v206, s98, v28
	v_mul_hi_u32 v207, v206, s101
	v_mul_u32_u24_e32 v207, 0x5700, v207
	v_sub_u32_e32 v206, v206, v207
	v_add_u32_e32 v206, s100, v206
	ds_read_u16 v28, v206
	v_mul_f32_e32 v57, v57, v35
	v_mul_f32_e32 v30, v30, v55
	v_mul_f32_e32 v32, v32, v55
	s_nop 1
	v_mov_b32_dpp v68, v56 row_mirror row_mask:0xf bank_mask:0xf
	v_mul_f32_e32 v30, v30, v37
	v_mul_f32_e32 v32, v32, v38
	v_lshl_add_u64 v[26:27], v[26:27], 0, s[20:21]
	s_waitcnt lgkmcnt(0)
	v_lshlrev_b32_e32 v39, 16, v39
	v_mul_f32_e32 v39, v57, v39
	v_bfe_u32 v57, v39, 16, 1
	v_add3_u32 v39, v39, v57, s61
	s_waitcnt lgkmcnt(0)
	v_lshlrev_b32_e32 v57, 16, v58
	s_waitcnt lgkmcnt(0)
	v_lshlrev_b32_e32 v55, 16, v59
	v_mul_f32_e32 v30, v30, v57
	v_mul_f32_e32 v32, v32, v55
	global_store_short_d16_hi v[24:25], v39, off offset:64
	v_bfe_u32 v57, v30, 16, 1
	v_bfe_u32 v55, v32, 16, 1
	v_add_u32_e32 v206, s99, v26
	v_mul_hi_u32 v207, v206, s101
	v_mul_u32_u24_e32 v207, 0x5700, v207
	v_sub_u32_e32 v206, v206, v207
	v_add_u32_e32 v206, s100, v206
	ds_read_u16 v39, v206 offset:64
	v_add3_u32 v30, v30, v57, s61
	v_add3_u32 v32, v32, v55, s61
	global_store_short_d16_hi v[24:25], v30, off offset:128
	global_store_short_d16_hi v[24:25], v32, off offset:192
	v_add_u32_e32 v206, s99, v26
	v_mul_hi_u32 v207, v206, s101
	v_mul_u32_u24_e32 v207, 0x5700, v207
	v_sub_u32_e32 v206, v206, v207
	v_add_u32_e32 v206, s100, v206
	ds_read_u16 v30, v206 offset:128
	v_add_u32_e32 v55, 24, v36
	v_add_u32_e32 v206, s99, v26
	v_mul_hi_u32 v207, v206, s101
	v_mul_u32_u24_e32 v207, 0x5700, v207
	v_sub_u32_e32 v206, v206, v207
	v_add_u32_e32 v206, s100, v206
	ds_read_u16 v32, v206 offset:192
	s_waitcnt lgkmcnt(0)
	v_add_f32_e32 v29, v56, v68
	ds_bpermute_b32 v56, v209, v29
	s_waitcnt lgkmcnt(0)
	v_add_f32_e32 v14, v29, v56
	v_fmamk_f32 v14, v14, 0x3c000000, v211
	v_mul_f32_e32 v29, 0x4f800000, v14
	v_cmp_gt_f32_e32 vcc, s58, v14
	v_mul_f32_e32 v56, v51, v51
	v_fmac_f32_e32 v56, v18, v18
	v_cndmask_b32_e32 v14, v14, v29, vcc
	v_sqrt_f32_e32 v29, v14
	v_fmac_f32_e32 v56, v52, v52
	v_fmac_f32_e32 v56, v22, v22
	v_add_u32_e32 v20, -1, v29
	v_fma_f32 v62, -v20, v29, v14
	v_cmp_ge_f32_e64 s[4:5], 0, v62
	v_add_u32_e32 v62, 1, v29
	s_waitcnt lgkmcnt(0)
	v_lshlrev_b32_e32 v30, 16, v30
	v_cndmask_b32_e64 v20, v29, v20, s[4:5]
	v_fma_f32 v29, -v62, v29, v14
	v_cmp_lt_f32_e64 s[4:5], 0, v29
	s_nop 1
	v_cndmask_b32_e64 v20, v20, v62, s[4:5]
	v_mul_f32_e32 v29, 0x37800000, v20
	v_cndmask_b32_e32 v20, v20, v29, vcc
	v_cmp_class_f32_e32 vcc, v14, v212
	s_nop 1
	v_cndmask_b32_e32 v14, v20, v14, vcc
	v_div_scale_f32 v20, s[4:5], v14, v14, s59
	v_rcp_f32_e32 v29, v20
	v_div_scale_f32 v62, vcc, s59, v14, s59
	v_fma_f32 v53, -v20, v29, 1.0
	v_fmac_f32_e32 v29, v53, v29
	s_nop 1
	v_mov_b32_dpp v53, v56 quad_perm:[1,0,3,2] row_mask:0xf bank_mask:0xf
	v_mul_f32_e32 v63, v62, v29
	v_fma_f32 v64, -v20, v63, v62
	v_fmac_f32_e32 v63, v64, v29
	v_fma_f32 v20, -v20, v63, v62
	s_waitcnt lgkmcnt(0)
	v_add_f32_e32 v53, v56, v53
	s_nop 1
	v_mov_b32_dpp v56, v53 quad_perm:[2,3,0,1] row_mask:0xf bank_mask:0xf
	v_div_fmas_f32 v20, v20, v29, v63
	v_div_fixup_f32 v20, v20, v14, s59
	s_waitcnt lgkmcnt(0)
	v_add_f32_e32 v24, v53, v56
	s_nop 1
	v_mov_b32_dpp v25, v24 row_half_mirror row_mask:0xf bank_mask:0xf
	s_waitcnt lgkmcnt(0)
; DI float bf2f(unsigned short u) { return __uint_as_float((unsigned)u << 16); }
; DI unsigned f2bf(float f) { unsigned u = __float_as_uint(f); return (u + 0x7fffu + ((u >> 16) & 1u)) >> 16; }
; DI int crow(int i, int hh) { return (i & 3) + 8 * (i >> 2) + 4 * hh; }
; DI void attn_unit(Ctx A_, LAS unsigned char* lds, int b, int h, int qb, float lam, int wave, int lane) {
;     ...
;     if (mp == 0) {
;         float ssq[16];
; #pragma unroll
;         for (int i = 0; i < 16; ++i) ssq[i] = 0.f;
; #pragma unroll
;         for (int nb = 0; nb < 4; ++nb)
; #pragma unroll
;             for (int i = 0; i < 16; ++i) { const float d = o[nb][i] - X2[(nb * 16 + i) * 64]; o[nb][i] = d; ssq[i] += d * d; }
; #pragma unroll
;         for (int i = 0; i < 16; ++i) {
;             float v = ssq[i];
; #pragma unroll
;             for (int x = 1; x < 32; x <<= 1) v += __shfl_xor(v, x);
;             ssq[i] = ONE_M_LAMINIT / sqrtf(v * (1.0f / 128.0f) + NORM_EPS);
;         }
; #pragma unroll
;         for (int nb = 0; nb < 4; ++nb) {
;             const float sn = SUB_NORM[nb * 32 + r_e];
; #pragma unroll
;             for (int i = 0; i < 16; ++i) {
;                 const size_t rw = (size_t)(rowq_e + crow(i, hh_e));
;                 Y_[rw * YLD + C_YA + h_e * 128 + nb * 32 + r_e] = (bf16)f2bf(o[nb][i] * ssq[i] * sn * bf2f(P[rw * PLD + C_ZA + h_e * 128 + nb * 32 + r_e]));
;             }
;         }
;     }
	v_add_f32_e32 v14, v24, v25
	v_mul_f32_e32 v24, v61, v20
	v_mul_f32_e32 v24, v24, v34
	v_lshlrev_b32_e32 v25, 16, v28
	v_mul_f32_e32 v24, v24, v25
	v_bfe_u32 v25, v24, 16, 1
	s_nop 1
	v_mov_b32_dpp v53, v14 row_mirror row_mask:0xf bank_mask:0xf
	v_add3_u32 v26, v24, v25, s61
	v_mad_i64_i32 v[24:25], s[4:5], v60, s62, v[4:5]
	global_store_short_d16_hi v[24:25], v26, off
	v_mad_i64_i32 v[26:27], s[4:5], v55, s57, v[6:7]
	v_lshl_add_u64 v[26:27], v[26:27], 0, s[0:1]
	v_lshl_add_u64 v[26:27], v[26:27], 0, v[2:3]
	v_add_co_u32_e32 v28, vcc, s60, v26
	s_waitcnt lgkmcnt(0)
	v_add_f32_e32 v14, v14, v53
	v_addc_co_u32_e32 v29, vcc, 0, v27, vcc
	v_add_u32_e32 v206, s98, v28
	v_mul_hi_u32 v207, v206, s101
	v_mul_u32_u24_e32 v207, 0x5700, v207
	v_sub_u32_e32 v206, v206, v207
	v_add_u32_e32 v206, s100, v206
	ds_read_u16 v28, v206
	v_sub_f32_e32 v29, v66, v19
	ds_bpermute_b32 v19, v209, v14
	v_mul_f32_e32 v53, v48, v48
	v_fmac_f32_e32 v53, v29, v29
	v_fmac_f32_e32 v53, v49, v49
	v_fmac_f32_e32 v53, v23, v23
	s_waitcnt lgkmcnt(0)
	v_add_f32_e32 v14, v14, v19
	v_fmamk_f32 v14, v14, 0x3c000000, v211
	v_mul_f32_e32 v15, 0x4f800000, v14
	v_cmp_gt_f32_e32 vcc, s58, v14
	s_nop 1
	v_mov_b32_dpp v56, v53 quad_perm:[1,0,3,2] row_mask:0xf bank_mask:0xf
	s_nop 0
	v_cndmask_b32_e32 v14, v14, v15, vcc
	v_sqrt_f32_e32 v15, v14
	s_nop 0
	v_add_u32_e32 v19, -1, v15
	v_fma_f32 v21, -v19, v15, v14
	v_cmp_ge_f32_e64 s[4:5], 0, v21
	v_add_u32_e32 v21, 1, v15
	s_nop 0
	v_cndmask_b32_e64 v19, v15, v19, s[4:5]
	v_fma_f32 v15, -v21, v15, v14
	v_cmp_lt_f32_e64 s[4:5], 0, v15
	s_nop 1
	v_cndmask_b32_e64 v15, v19, v21, s[4:5]
	v_mul_f32_e32 v19, 0x37800000, v15
	v_cndmask_b32_e32 v15, v15, v19, vcc
	v_cmp_class_f32_e32 vcc, v14, v212
	s_nop 1
	v_cndmask_b32_e32 v19, v15, v14, vcc
	v_lshl_add_u64 v[14:15], v[26:27], 0, s[20:21]
	v_mul_f32_e32 v26, v54, v20
	v_mul_f32_e32 v26, v26, v35
	v_lshlrev_b32_e32 v27, 16, v39
	v_mul_f32_e32 v26, v26, v27
	v_bfe_u32 v27, v26, 16, 1
	v_add3_u32 v26, v26, v27, s61
	global_store_short_d16_hi v[24:25], v26, off offset:64
	v_mul_f32_e32 v27, v31, v20
	v_add_u32_e32 v206, s99, v14
	v_mul_hi_u32 v207, v206, s101
	v_mul_u32_u24_e32 v207, 0x5700, v207
	v_sub_u32_e32 v206, v206, v207
	v_add_u32_e32 v206, s100, v206
	ds_read_u16 v26, v206 offset:64
	v_mul_f32_e32 v27, v27, v37
	v_mul_f32_e32 v27, v27, v30
	v_bfe_u32 v30, v27, 16, 1
	v_add3_u32 v27, v27, v30, s61
	global_store_short_d16_hi v[24:25], v27, off offset:128
	v_mul_f32_e32 v20, v33, v20
	v_add_u32_e32 v206, s99, v14
	v_mul_hi_u32 v207, v206, s101
	v_mul_u32_u24_e32 v207, 0x5700, v207
	v_sub_u32_e32 v206, v206, v207
	v_add_u32_e32 v206, s100, v206
	ds_read_u16 v27, v206 offset:128
	v_mul_f32_e32 v20, v20, v38
	s_waitcnt lgkmcnt(0)
	v_lshlrev_b32_e32 v30, 16, v32
	v_mul_f32_e32 v20, v20, v30
	v_bfe_u32 v30, v20, 16, 1
	v_add3_u32 v20, v20, v30, s61
	global_store_short_d16_hi v[24:25], v20, off offset:192
	v_add_u32_e32 v206, s99, v14
	v_mul_hi_u32 v207, v206, s101
	v_mul_u32_u24_e32 v207, 0x5700, v207
	v_sub_u32_e32 v206, v206, v207
	v_add_u32_e32 v206, s100, v206
	ds_read_u16 v24, v206 offset:192
	v_div_scale_f32 v21, s[4:5], v19, v19, s59
	v_rcp_f32_e32 v50, v21
	v_div_scale_f32 v20, vcc, s59, v19, s59
	v_sub_f32_e32 v32, v47, v8
	v_fma_f32 v14, -v21, v50, 1.0
	v_fmac_f32_e32 v50, v14, v50
	s_waitcnt lgkmcnt(0)
	v_add_f32_e32 v14, v53, v56
	s_nop 1
	v_mov_b32_dpp v15, v14 quad_perm:[2,3,0,1] row_mask:0xf bank_mask:0xf
	v_mul_f32_e32 v25, v20, v50
	v_fma_f32 v30, -v21, v25, v20
	v_fmac_f32_e32 v25, v30, v50
	v_fma_f32 v20, -v21, v25, v20
	s_waitcnt lgkmcnt(0)
	v_add_f32_e32 v14, v14, v15
	s_nop 1
	v_mov_b32_dpp v15, v14 row_half_mirror row_mask:0xf bank_mask:0xf
	v_div_fmas_f32 v20, v20, v50, v25
	v_div_fixup_f32 v25, v20, v19, s59
	v_mul_f32_e32 v39, v51, v25
	v_mul_f32_e32 v39, v39, v35
	s_waitcnt lgkmcnt(0)
	v_add_f32_e32 v30, v14, v15
	v_mul_f32_e32 v14, v18, v25
	v_mul_f32_e32 v14, v14, v34
	s_waitcnt lgkmcnt(0)
	v_lshlrev_b32_e32 v15, 16, v28
	v_mul_f32_e32 v14, v14, v15
	v_bfe_u32 v15, v14, 16, 1
	v_add3_u32 v18, v14, v15, s61
	v_mad_i64_i32 v[14:15], s[4:5], v55, s62, v[4:5]
	v_add_u32_e32 v28, 25, v36
	global_store_short_d16_hi v[14:15], v18, off
	v_mad_i64_i32 v[18:19], s[4:5], v28, s57, v[6:7]
	v_lshl_add_u64 v[18:19], v[18:19], 0, s[0:1]
	v_lshl_add_u64 v[18:19], v[18:19], 0, v[2:3]
	v_add_co_u32_e32 v20, vcc, s60, v18
	v_mul_f32_e32 v22, v22, v25
	s_nop 0
	v_addc_co_u32_e32 v21, vcc, 0, v19, vcc
	v_add_u32_e32 v206, s98, v20
	v_mul_hi_u32 v207, v206, s101
	v_mul_u32_u24_e32 v207, 0x5700, v207
	v_sub_u32_e32 v206, v206, v207
	v_add_u32_e32 v206, s100, v206
	ds_read_u16 v20, v206
	v_lshl_add_u64 v[18:19], v[18:19], 0, s[20:21]
	v_mul_f32_e32 v22, v22, v38
	s_nop 1
	v_mov_b32_dpp v31, v30 row_mirror row_mask:0xf bank_mask:0xf
	s_waitcnt lgkmcnt(0)
	v_lshlrev_b32_e32 v26, 16, v26
	v_mul_f32_e32 v26, v39, v26
	v_bfe_u32 v39, v26, 16, 1
	v_add3_u32 v26, v26, v39, s61
	global_store_short_d16_hi v[14:15], v26, off offset:64
	v_mul_f32_e32 v39, v52, v25
	v_add_u32_e32 v206, s99, v18
	v_mul_hi_u32 v207, v206, s101
	v_mul_u32_u24_e32 v207, 0x5700, v207
	v_sub_u32_e32 v206, v206, v207
	v_add_u32_e32 v206, s100, v206
	ds_read_u16 v26, v206 offset:64
	v_mul_f32_e32 v39, v39, v37
	s_waitcnt lgkmcnt(0)
	v_lshlrev_b32_e32 v27, 16, v27
	v_mul_f32_e32 v27, v39, v27
	v_bfe_u32 v39, v27, 16, 1
	v_add3_u32 v27, v27, v39, s61
	global_store_short_d16_hi v[14:15], v27, off offset:128
	v_add_u32_e32 v206, s99, v18
	v_mul_hi_u32 v207, v206, s101
	v_mul_u32_u24_e32 v207, 0x5700, v207
	v_sub_u32_e32 v206, v206, v207
	v_add_u32_e32 v206, s100, v206
	ds_read_u16 v27, v206 offset:128
	s_waitcnt lgkmcnt(0)
; DI float bf2f(unsigned short u) { return __uint_as_float((unsigned)u << 16); }
; DI unsigned f2bf(float f) { unsigned u = __float_as_uint(f); return (u + 0x7fffu + ((u >> 16) & 1u)) >> 16; }
; DI int crow(int i, int hh) { return (i & 3) + 8 * (i >> 2) + 4 * hh; }
; DI void attn_unit(Ctx A_, LAS unsigned char* lds, int b, int h, int qb, float lam, int wave, int lane) {
;     ...
;     if (mp == 0) {
;         float ssq[16];
; #pragma unroll
;         for (int i = 0; i < 16; ++i) ssq[i] = 0.f;
; #pragma unroll
;         for (int nb = 0; nb < 4; ++nb)
; #pragma unroll
;             for (int i = 0; i < 16; ++i) { const float d = o[nb][i] - X2[(nb * 16 + i) * 64]; o[nb][i] = d; ssq[i] += d * d; }
; #pragma unroll
;         for (int i = 0; i < 16; ++i) {
;             float v = ssq[i];
; #pragma unroll
;             for (int x = 1; x < 32; x <<= 1) v += __shfl_xor(v, x);
;             ssq[i] = ONE_M_LAMINIT / sqrtf(v * (1.0f / 128.0f) + NORM_EPS);
;         }
; #pragma unroll
;         for (int nb = 0; nb < 4; ++nb) {
;             const float sn = SUB_NORM[nb * 32 + r_e];
; #pragma unroll
;             for (int i = 0; i < 16; ++i) {
;                 const size_t rw = (size_t)(rowq_e + crow(i, hh_e));
;                 Y_[rw * YLD + C_YA + h_e * 128 + nb * 32 + r_e] = (bf16)f2bf(o[nb][i] * ssq[i] * sn * bf2f(P[rw * PLD + C_ZA + h_e * 128 + nb * 32 + r_e]));
;             }
;         }
;     }
	v_lshlrev_b32_e32 v24, 16, v24
	v_mul_f32_e32 v22, v22, v24
	v_bfe_u32 v24, v22, 16, 1
	v_add3_u32 v22, v22, v24, s61
	global_store_short_d16_hi v[14:15], v22, off offset:192
	v_add_u32_e32 v206, s99, v18
	v_mul_hi_u32 v207, v206, s101
	v_mul_u32_u24_e32 v207, 0x5700, v207
	v_sub_u32_e32 v206, v206, v207
	v_add_u32_e32 v206, s100, v206
	ds_read_u16 v22, v206 offset:192
	s_waitcnt lgkmcnt(0)
	v_add_f32_e32 v21, v30, v31
	ds_bpermute_b32 v30, v209, v21
	v_sub_f32_e32 v31, v45, v10
	v_mul_f32_e32 v10, v31, v31
	v_fmac_f32_e32 v10, v16, v16
	v_fmac_f32_e32 v10, v12, v12
	s_waitcnt lgkmcnt(0)
	v_add_f32_e32 v21, v21, v30
	v_fmamk_f32 v21, v21, 0x3c000000, v211
	v_mul_f32_e32 v30, 0x4f800000, v21
	v_cmp_gt_f32_e32 vcc, s58, v21
	v_fmac_f32_e32 v10, v32, v32
	s_nop 1
	v_mov_b32_dpp v18, v10 quad_perm:[1,0,3,2] row_mask:0xf bank_mask:0xf
	v_cndmask_b32_e32 v21, v21, v30, vcc
	v_sqrt_f32_e32 v30, v21
	v_add_u32_e32 v25, 26, v36
	s_waitcnt lgkmcnt(0)
	v_add_f32_e32 v10, v10, v18
	v_add_u32_e32 v8, -1, v30
	v_fma_f32 v33, -v8, v30, v21
	v_cmp_ge_f32_e64 s[4:5], 0, v33
	v_add_u32_e32 v33, 1, v30
	v_fma_f32 v14, -v33, v30, v21
	v_cndmask_b32_e64 v8, v30, v8, s[4:5]
	v_cmp_lt_f32_e64 s[4:5], 0, v14
	s_nop 1
	v_mov_b32_dpp v18, v10 quad_perm:[2,3,0,1] row_mask:0xf bank_mask:0xf
	s_waitcnt lgkmcnt(0)
	v_add_f32_e32 v10, v10, v18
	v_cndmask_b32_e64 v8, v8, v33, s[4:5]
	v_mul_f32_e32 v14, 0x37800000, v8
	v_cndmask_b32_e32 v8, v8, v14, vcc
	v_cmp_class_f32_e32 vcc, v21, v212
	s_nop 1
	v_mov_b32_dpp v18, v10 row_half_mirror row_mask:0xf bank_mask:0xf
	s_waitcnt lgkmcnt(0)
	v_add_f32_e32 v10, v10, v18
	v_cndmask_b32_e32 v8, v8, v21, vcc
	v_div_scale_f32 v14, s[4:5], v8, v8, s59
	v_rcp_f32_e32 v15, v14
	s_waitcnt lgkmcnt(0)
	v_lshlrev_b32_e32 v22, 16, v22
	v_fma_f32 v19, -v14, v15, 1.0
	v_fmac_f32_e32 v15, v19, v15
	v_div_scale_f32 v19, vcc, s59, v8, s59
	v_mul_f32_e32 v21, v19, v15
	v_fma_f32 v24, -v14, v21, v19
	v_fmac_f32_e32 v21, v24, v15
	v_fma_f32 v14, -v14, v21, v19
	v_div_fmas_f32 v14, v14, v15, v21
	v_div_fixup_f32 v8, v14, v8, s59
	v_mul_f32_e32 v14, v29, v8
	v_mul_f32_e32 v14, v14, v34
	v_lshlrev_b32_e32 v15, 16, v20
	v_mul_f32_e32 v14, v14, v15
	v_bfe_u32 v15, v14, 16, 1
	s_nop 1
	v_mov_b32_dpp v24, v10 row_mirror row_mask:0xf bank_mask:0xf
	v_add3_u32 v18, v14, v15, s61
	v_mad_i64_i32 v[14:15], s[4:5], v28, s62, v[4:5]
	global_store_short_d16_hi v[14:15], v18, off
	v_mad_i64_i32 v[18:19], s[4:5], v25, s57, v[6:7]
	v_lshl_add_u64 v[18:19], v[18:19], 0, s[0:1]
	v_lshl_add_u64 v[18:19], v[18:19], 0, v[2:3]
	v_add_co_u32_e32 v20, vcc, s60, v18
	s_waitcnt lgkmcnt(0)
	v_add_f32_e32 v10, v10, v24
	v_addc_co_u32_e32 v21, vcc, 0, v19, vcc
	v_add_u32_e32 v206, s98, v20
	v_mul_hi_u32 v207, v206, s101
	v_mul_u32_u24_e32 v207, 0x5700, v207
	v_sub_u32_e32 v206, v206, v207
	v_add_u32_e32 v206, s100, v206
	ds_read_u16 v20, v206
	ds_bpermute_b32 v21, v209, v10
	v_sub_f32_e32 v24, v43, v11
	s_waitcnt lgkmcnt(0)
	v_add_f32_e32 v10, v10, v21
	v_fmamk_f32 v21, v10, 0x3c000000, v211
	v_lshl_add_u64 v[10:11], v[18:19], 0, s[20:21]
	v_mul_f32_e32 v18, v48, v8
	v_mul_f32_e32 v18, v18, v35
	v_lshlrev_b32_e32 v19, 16, v26
	v_mul_f32_e32 v18, v18, v19
	v_bfe_u32 v19, v18, 16, 1
	v_add3_u32 v18, v18, v19, s61
	global_store_short_d16_hi v[14:15], v18, off offset:64
	v_mul_f32_e32 v19, v49, v8
	v_add_u32_e32 v206, s99, v10
	v_mul_hi_u32 v207, v206, s101
	v_mul_u32_u24_e32 v207, 0x5700, v207
	v_sub_u32_e32 v206, v206, v207
	v_add_u32_e32 v206, s100, v206
	ds_read_u16 v18, v206 offset:64
	v_mul_f32_e32 v19, v19, v37
	v_lshlrev_b32_e32 v26, 16, v27
	v_mul_f32_e32 v19, v19, v26
	v_bfe_u32 v26, v19, 16, 1
	v_add3_u32 v19, v19, v26, s61
	global_store_short_d16_hi v[14:15], v19, off offset:128
	v_mul_f32_e32 v8, v23, v8
	v_add_u32_e32 v206, s99, v10
	v_mul_hi_u32 v207, v206, s101
	v_mul_u32_u24_e32 v207, 0x5700, v207
	v_sub_u32_e32 v206, v206, v207
	v_add_u32_e32 v206, s100, v206
	ds_read_u16 v19, v206 offset:128
	v_mul_f32_e32 v8, v8, v38
	v_mul_f32_e32 v8, v8, v22
	v_bfe_u32 v22, v8, 16, 1
	v_add3_u32 v8, v8, v22, s61
	global_store_short_d16_hi v[14:15], v8, off offset:192
	v_add_u32_e32 v206, s99, v10
	v_mul_hi_u32 v207, v206, s101
	v_mul_u32_u24_e32 v207, 0x5700, v207
	v_sub_u32_e32 v206, v206, v207
	v_add_u32_e32 v206, s100, v206
	ds_read_u16 v10, v206 offset:192
	v_mul_f32_e32 v8, 0x4f800000, v21
	v_cmp_gt_f32_e32 vcc, s58, v21
	v_mul_f32_e32 v14, v24, v24
	v_fmac_f32_e32 v14, v17, v17
	v_cndmask_b32_e32 v8, v21, v8, vcc
	v_sqrt_f32_e32 v11, v8
	v_fmac_f32_e32 v14, v13, v13
	v_add_u32_e32 v15, -1, v11
	v_fma_f32 v21, -v15, v11, v8
	v_cmp_ge_f32_e64 s[4:5], 0, v21
	v_add_u32_e32 v21, 1, v11
	s_waitcnt lgkmcnt(0)
	v_lshlrev_b32_e32 v18, 16, v18
	v_cndmask_b32_e64 v15, v11, v15, s[4:5]
	v_fma_f32 v11, -v21, v11, v8
	v_cmp_lt_f32_e64 s[4:5], 0, v11
	s_waitcnt lgkmcnt(0)
; DI float bf2f(unsigned short u) { return __uint_as_float((unsigned)u << 16); }
; DI unsigned f2bf(float f) { unsigned u = __float_as_uint(f); return (u + 0x7fffu + ((u >> 16) & 1u)) >> 16; }
; DI int crow(int i, int hh) { return (i & 3) + 8 * (i >> 2) + 4 * hh; }
; DI int tid_now() { int t; asm volatile("v_mov_b32 %0, %1" : "=v"(t) : "v"((int)threadIdx.x)); return t; }
; #define Q_NEXT(k, id) do { if (tid == 0) qw[qit & 1] = __hip_atomic_fetch_add(qctr + 64 * (k), 1u, __ATOMIC_RELAXED, __HIP_MEMORY_SCOPE_AGENT); __syncthreads(); \
;         id = __builtin_amdgcn_readfirstlane((int)qw[qit & 1]); ++qit; } while (0)
; DI void attn_unit(Ctx A_, LAS unsigned char* lds, int b, int h, int qb, float lam, int wave, int lane) {
;     ...
;     if (mp == 0) {
;         float ssq[16];
; #pragma unroll
;         for (int i = 0; i < 16; ++i) ssq[i] = 0.f;
; #pragma unroll
;         for (int nb = 0; nb < 4; ++nb)
; #pragma unroll
;             for (int i = 0; i < 16; ++i) { const float d = o[nb][i] - X2[(nb * 16 + i) * 64]; o[nb][i] = d; ssq[i] += d * d; }
; #pragma unroll
;         for (int i = 0; i < 16; ++i) {
;             float v = ssq[i];
; #pragma unroll
;             for (int x = 1; x < 32; x <<= 1) v += __shfl_xor(v, x);
;             ssq[i] = ONE_M_LAMINIT / sqrtf(v * (1.0f / 128.0f) + NORM_EPS);
;         }
; #pragma unroll
;         for (int nb = 0; nb < 4; ++nb) {
;             const float sn = SUB_NORM[nb * 32 + r_e];
; #pragma unroll
;             for (int i = 0; i < 16; ++i) {
;                 const size_t rw = (size_t)(rowq_e + crow(i, hh_e));
;                 Y_[rw * YLD + C_YA + h_e * 128 + nb * 32 + r_e] = (bf16)f2bf(o[nb][i] * ssq[i] * sn * bf2f(P[rw * PLD + C_ZA + h_e * 128 + nb * 32 + r_e]));
;             }
;         }
;     }
; __global__ void __launch_bounds__(512, 2) fwd(Args args) {
;     ...
;         for (;;) { int id; Q_NEXT(2, id); if (id >= 2048) break; const int lane = tid_now() & 63; fa::attn_unit(A_, lds, id >> 8, (id >> 5) & 7, 31 - (id & 31), lam, wave, lane); }
	v_lshlrev_b32_e32 v10, 16, v10
	v_cndmask_b32_e64 v11, v15, v21, s[4:5]
	v_mul_f32_e32 v15, 0x37800000, v11
	v_cndmask_b32_e32 v11, v11, v15, vcc
	v_cmp_class_f32_e32 vcc, v8, v212
	v_sub_f32_e32 v21, v41, v9
	v_fmac_f32_e32 v14, v21, v21
	v_cndmask_b32_e32 v8, v11, v8, vcc
	v_div_scale_f32 v11, s[4:5], v8, v8, s59
	v_rcp_f32_e32 v15, v11
	v_div_scale_f32 v22, vcc, s59, v8, s59
	v_fma_f32 v9, -v11, v15, 1.0
	v_fmac_f32_e32 v15, v9, v15
	s_nop 1
	v_mov_b32_dpp v9, v14 quad_perm:[1,0,3,2] row_mask:0xf bank_mask:0xf
	v_mul_f32_e32 v23, v22, v15
	v_fma_f32 v26, -v11, v23, v22
	v_fmac_f32_e32 v23, v26, v15
	v_fma_f32 v11, -v11, v23, v22
	s_waitcnt lgkmcnt(0)
	v_add_f32_e32 v9, v14, v9
	s_nop 1
	v_mov_b32_dpp v14, v9 quad_perm:[2,3,0,1] row_mask:0xf bank_mask:0xf
	v_div_fmas_f32 v11, v11, v15, v23
	v_div_fixup_f32 v11, v11, v8, s59
	v_mul_f32_e32 v8, v16, v11
	v_mul_f32_e32 v8, v34, v8
	s_waitcnt lgkmcnt(0)
	v_add_f32_e32 v14, v9, v14
	v_lshlrev_b32_e32 v9, 16, v20
	v_mul_f32_e32 v8, v8, v9
	v_bfe_u32 v9, v8, 16, 1
	v_add3_u32 v16, v8, v9, s61
	v_mad_i64_i32 v[8:9], s[4:5], v25, s62, v[4:5]
	global_store_short_d16_hi v[8:9], v16, off
	v_add_u32_e32 v16, 27, v36
	v_mad_i64_i32 v[6:7], s[4:5], v16, s57, v[6:7]
	v_lshl_add_u64 v[6:7], v[6:7], 0, s[0:1]
	v_lshl_add_u64 v[2:3], v[6:7], 0, v[2:3]
	v_lshl_add_u64 v[6:7], v[2:3], 0, s[20:21]
	v_add_co_u32_e32 v2, vcc, s60, v2
	s_nop 1
	v_mov_b32_dpp v15, v14 row_half_mirror row_mask:0xf bank_mask:0xf
	s_nop 0
	v_addc_co_u32_e32 v3, vcc, 0, v3, vcc
	v_add_u32_e32 v206, s98, v2
	v_mul_hi_u32 v207, v206, s101
	v_mul_u32_u24_e32 v207, 0x5700, v207
	v_sub_u32_e32 v206, v206, v207
	v_add_u32_e32 v206, s100, v206
	ds_read_u16 v2, v206
	v_mul_f32_e32 v3, v31, v11
	v_mul_f32_e32 v3, v3, v35
	v_mul_f32_e32 v3, v3, v18
	v_bfe_u32 v18, v3, 16, 1
	v_add3_u32 v3, v3, v18, s61
	global_store_short_d16_hi v[8:9], v3, off offset:64
	v_mul_f32_e32 v3, v12, v11
	v_add_u32_e32 v206, s99, v6
	v_mul_hi_u32 v207, v206, s101
	v_mul_u32_u24_e32 v207, 0x5700, v207
	v_sub_u32_e32 v206, v206, v207
	v_add_u32_e32 v206, s100, v206
	ds_read_u16 v18, v206 offset:64
	v_mul_f32_e32 v3, v3, v37
	v_lshlrev_b32_e32 v12, 16, v19
	v_mul_f32_e32 v3, v3, v12
	v_bfe_u32 v12, v3, 16, 1
	v_add3_u32 v3, v3, v12, s61
	global_store_short_d16_hi v[8:9], v3, off offset:128
	v_mul_f32_e32 v3, v32, v11
	v_add_u32_e32 v206, s99, v6
	v_mul_hi_u32 v207, v206, s101
	v_mul_u32_u24_e32 v207, 0x5700, v207
	v_sub_u32_e32 v206, v206, v207
	v_add_u32_e32 v206, s100, v206
	ds_read_u16 v12, v206 offset:128
	v_mul_f32_e32 v3, v3, v38
	v_mul_f32_e32 v3, v3, v10
	v_bfe_u32 v10, v3, 16, 1
	v_add3_u32 v3, v3, v10, s61
	global_store_short_d16_hi v[8:9], v3, off offset:192
	v_add_u32_e32 v206, s99, v6
	v_mul_hi_u32 v207, v206, s101
	v_mul_u32_u24_e32 v207, 0x5700, v207
	v_sub_u32_e32 v206, v206, v207
	v_add_u32_e32 v206, s100, v206
	ds_read_u16 v6, v206 offset:192
	s_waitcnt lgkmcnt(0)
	v_add_f32_e32 v3, v14, v15
	s_nop 1
	v_mov_b32_dpp v7, v3 row_mirror row_mask:0xf bank_mask:0xf
	s_waitcnt lgkmcnt(0)
	v_add_f32_e32 v3, v3, v7
	ds_bpermute_b32 v7, v209, v3
	s_waitcnt lgkmcnt(0)
	v_add_f32_e32 v3, v3, v7
	v_fmamk_f32 v3, v3, 0x3c000000, v211
	v_mul_f32_e32 v7, 0x4f800000, v3
	v_cmp_gt_f32_e32 vcc, s58, v3
	s_waitcnt lgkmcnt(0)
	v_lshlrev_b32_e32 v2, 16, v2
	v_cndmask_b32_e32 v3, v3, v7, vcc
	v_sqrt_f32_e32 v7, v3
	s_nop 0
	v_add_u32_e32 v8, -1, v7
	v_fma_f32 v9, -v8, v7, v3
	v_cmp_ge_f32_e64 s[4:5], 0, v9
	v_add_u32_e32 v9, 1, v7
	s_nop 0
	v_cndmask_b32_e64 v8, v7, v8, s[4:5]
	v_fma_f32 v7, -v9, v7, v3
	v_cmp_lt_f32_e64 s[4:5], 0, v7
	s_nop 1
	v_cndmask_b32_e64 v7, v8, v9, s[4:5]
	v_mul_f32_e32 v8, 0x37800000, v7
	v_cndmask_b32_e32 v7, v7, v8, vcc
	v_cmp_class_f32_e32 vcc, v3, v212
	s_nop 1
	v_cndmask_b32_e32 v3, v7, v3, vcc
	v_div_scale_f32 v7, s[0:1], v3, v3, s59
	v_rcp_f32_e32 v8, v7
	s_nop 0
	v_fma_f32 v9, -v7, v8, 1.0
	v_fmac_f32_e32 v8, v9, v8
	v_div_scale_f32 v9, vcc, s59, v3, s59
	v_mul_f32_e32 v10, v9, v8
	v_fma_f32 v11, -v7, v10, v9
	v_fmac_f32_e32 v10, v11, v8
	v_fma_f32 v7, -v7, v10, v9
	v_div_fmas_f32 v7, v7, v8, v10
	v_div_fixup_f32 v7, v7, v3, s59
	v_mul_f32_e32 v3, v17, v7
	v_mul_f32_e32 v3, v34, v3
	v_mul_f32_e32 v2, v3, v2
	v_bfe_u32 v3, v2, 16, 1
	v_add3_u32 v8, v2, v3, s61
	v_mad_i64_i32 v[2:3], s[0:1], v16, s62, v[4:5]
	v_mul_f32_e32 v4, v24, v7
	v_mul_f32_e32 v4, v4, v35
	s_waitcnt lgkmcnt(0)
	v_lshlrev_b32_e32 v5, 16, v18
	v_mul_f32_e32 v4, v4, v5
	v_bfe_u32 v5, v4, 16, 1
	v_add3_u32 v4, v4, v5, s61
	global_store_short_d16_hi v[2:3], v4, off offset:64
	v_mul_f32_e32 v4, v13, v7
	v_mul_f32_e32 v4, v4, v37
	s_waitcnt lgkmcnt(0)
	v_lshlrev_b32_e32 v5, 16, v12
	v_mul_f32_e32 v4, v4, v5
	v_bfe_u32 v5, v4, 16, 1
	v_add3_u32 v4, v4, v5, s61
	global_store_short_d16_hi v[2:3], v4, off offset:128
	v_mul_f32_e32 v4, v21, v7
	v_mul_f32_e32 v4, v4, v38
	s_waitcnt lgkmcnt(0)
	v_lshlrev_b32_e32 v5, 16, v6
	v_mul_f32_e32 v4, v4, v5
	v_bfe_u32 v5, v4, 16, 1
	v_add3_u32 v4, v4, v5, s61
	global_store_short_d16_hi v[2:3], v8, off
	global_store_short_d16_hi v[2:3], v4, off offset:192
	s_branch .LBB0_862
